# silu(c) prologue loop: 16 loads batched; epilogue stores of gate-up/out-proj/down lane-transposed (ds_bpermute) for 64B-contiguous lane groups
# speedup vs baseline: 1.0132x; 1.0067x over previous
; __device__ __forceinline__ void prologue(const Args& a, LAS unsigned char* lds) {
;     ...
;         for (int i = tid; i < NB * DM; i += 512) { const float v = a.c[i]; sc[i] = v / (1.0f + __expf(-v)); }
.LBB0_7:
	global_load_dword v208, v[2:3], off
	v_lshl_add_u64 v[2:3], v[2:3], 0, s[8:9]
	global_load_dword v209, v[2:3], off
	v_lshl_add_u64 v[2:3], v[2:3], 0, s[8:9]
	global_load_dword v210, v[2:3], off
	v_lshl_add_u64 v[2:3], v[2:3], 0, s[8:9]
	global_load_dword v211, v[2:3], off
	v_lshl_add_u64 v[2:3], v[2:3], 0, s[8:9]
	global_load_dword v212, v[2:3], off
	v_lshl_add_u64 v[2:3], v[2:3], 0, s[8:9]
	global_load_dword v213, v[2:3], off
	v_lshl_add_u64 v[2:3], v[2:3], 0, s[8:9]
	global_load_dword v214, v[2:3], off
	v_lshl_add_u64 v[2:3], v[2:3], 0, s[8:9]
	global_load_dword v215, v[2:3], off
	v_lshl_add_u64 v[2:3], v[2:3], 0, s[8:9]
	global_load_dword v216, v[2:3], off
	v_lshl_add_u64 v[2:3], v[2:3], 0, s[8:9]
	global_load_dword v217, v[2:3], off
	v_lshl_add_u64 v[2:3], v[2:3], 0, s[8:9]
	global_load_dword v218, v[2:3], off
	v_lshl_add_u64 v[2:3], v[2:3], 0, s[8:9]
	global_load_dword v219, v[2:3], off
	v_lshl_add_u64 v[2:3], v[2:3], 0, s[8:9]
	global_load_dword v220, v[2:3], off
	v_lshl_add_u64 v[2:3], v[2:3], 0, s[8:9]
	global_load_dword v221, v[2:3], off
	v_lshl_add_u64 v[2:3], v[2:3], 0, s[8:9]
	global_load_dword v222, v[2:3], off
	v_lshl_add_u64 v[2:3], v[2:3], 0, s[8:9]
	global_load_dword v223, v[2:3], off
	v_lshl_add_u64 v[2:3], v[2:3], 0, s[8:9]
	s_waitcnt vmcnt(15)
	v_mul_f32_e32 v6, 0xbfb8aa3b, v208
	v_exp_f32_e32 v6, v6
	s_nop 0
	v_add_f32_e32 v6, 1.0, v6
	v_div_scale_f32 v7, s[12:13], v6, v6, v208
	v_rcp_f32_e32 v8, v7
	v_div_scale_f32 v9, vcc, v208, v6, v208
	v_fma_f32 v10, -v7, v8, 1.0
	v_fmac_f32_e32 v8, v10, v8
	v_mul_f32_e32 v10, v9, v8
	v_fma_f32 v11, -v7, v10, v9
	v_fmac_f32_e32 v10, v11, v8
	v_fma_f32 v7, -v7, v10, v9
	v_div_fmas_f32 v7, v7, v8, v10
	v_div_fixup_f32 v208, v7, v6, v208
	ds_write_b32 v4, v208
	v_add_u32_e32 v4, 0x800, v4
	s_waitcnt vmcnt(14)
	v_mul_f32_e32 v6, 0xbfb8aa3b, v209
	v_exp_f32_e32 v6, v6
	s_nop 0
	v_add_f32_e32 v6, 1.0, v6
	v_div_scale_f32 v7, s[12:13], v6, v6, v209
	v_rcp_f32_e32 v8, v7
	v_div_scale_f32 v9, vcc, v209, v6, v209
	v_fma_f32 v10, -v7, v8, 1.0
	v_fmac_f32_e32 v8, v10, v8
	v_mul_f32_e32 v10, v9, v8
	v_fma_f32 v11, -v7, v10, v9
	v_fmac_f32_e32 v10, v11, v8
	v_fma_f32 v7, -v7, v10, v9
	v_div_fmas_f32 v7, v7, v8, v10
	v_div_fixup_f32 v209, v7, v6, v209
	ds_write_b32 v4, v209
	v_add_u32_e32 v4, 0x800, v4
	s_waitcnt vmcnt(13)
	v_mul_f32_e32 v6, 0xbfb8aa3b, v210
	v_exp_f32_e32 v6, v6
	s_nop 0
	v_add_f32_e32 v6, 1.0, v6
	v_div_scale_f32 v7, s[12:13], v6, v6, v210
	v_rcp_f32_e32 v8, v7
	v_div_scale_f32 v9, vcc, v210, v6, v210
	v_fma_f32 v10, -v7, v8, 1.0
	v_fmac_f32_e32 v8, v10, v8
	v_mul_f32_e32 v10, v9, v8
	v_fma_f32 v11, -v7, v10, v9
	v_fmac_f32_e32 v10, v11, v8
	v_fma_f32 v7, -v7, v10, v9
	v_div_fmas_f32 v7, v7, v8, v10
	v_div_fixup_f32 v210, v7, v6, v210
	ds_write_b32 v4, v210
	v_add_u32_e32 v4, 0x800, v4
	s_waitcnt vmcnt(12)
	v_mul_f32_e32 v6, 0xbfb8aa3b, v211
	v_exp_f32_e32 v6, v6
	s_nop 0
	v_add_f32_e32 v6, 1.0, v6
	v_div_scale_f32 v7, s[12:13], v6, v6, v211
	v_rcp_f32_e32 v8, v7
	v_div_scale_f32 v9, vcc, v211, v6, v211
	v_fma_f32 v10, -v7, v8, 1.0
	v_fmac_f32_e32 v8, v10, v8
	v_mul_f32_e32 v10, v9, v8
	v_fma_f32 v11, -v7, v10, v9
	v_fmac_f32_e32 v10, v11, v8
	v_fma_f32 v7, -v7, v10, v9
	v_div_fmas_f32 v7, v7, v8, v10
	v_div_fixup_f32 v211, v7, v6, v211
	ds_write_b32 v4, v211
	v_add_u32_e32 v4, 0x800, v4
	s_waitcnt vmcnt(11)
	v_mul_f32_e32 v6, 0xbfb8aa3b, v212
	v_exp_f32_e32 v6, v6
	s_nop 0
	v_add_f32_e32 v6, 1.0, v6
	v_div_scale_f32 v7, s[12:13], v6, v6, v212
	v_rcp_f32_e32 v8, v7
	v_div_scale_f32 v9, vcc, v212, v6, v212
	v_fma_f32 v10, -v7, v8, 1.0
	v_fmac_f32_e32 v8, v10, v8
	v_mul_f32_e32 v10, v9, v8
	v_fma_f32 v11, -v7, v10, v9
	v_fmac_f32_e32 v10, v11, v8
	v_fma_f32 v7, -v7, v10, v9
	v_div_fmas_f32 v7, v7, v8, v10
	v_div_fixup_f32 v212, v7, v6, v212
	ds_write_b32 v4, v212
	v_add_u32_e32 v4, 0x800, v4
	s_waitcnt vmcnt(10)
	v_mul_f32_e32 v6, 0xbfb8aa3b, v213
	v_exp_f32_e32 v6, v6
	s_nop 0
	v_add_f32_e32 v6, 1.0, v6
	v_div_scale_f32 v7, s[12:13], v6, v6, v213
	v_rcp_f32_e32 v8, v7
	v_div_scale_f32 v9, vcc, v213, v6, v213
	v_fma_f32 v10, -v7, v8, 1.0
	v_fmac_f32_e32 v8, v10, v8
	v_mul_f32_e32 v10, v9, v8
	v_fma_f32 v11, -v7, v10, v9
	v_fmac_f32_e32 v10, v11, v8
	v_fma_f32 v7, -v7, v10, v9
	v_div_fmas_f32 v7, v7, v8, v10
	v_div_fixup_f32 v213, v7, v6, v213
	ds_write_b32 v4, v213
	v_add_u32_e32 v4, 0x800, v4
	s_waitcnt vmcnt(9)
	v_mul_f32_e32 v6, 0xbfb8aa3b, v214
	v_exp_f32_e32 v6, v6
	s_nop 0
	v_add_f32_e32 v6, 1.0, v6
	v_div_scale_f32 v7, s[12:13], v6, v6, v214
	v_rcp_f32_e32 v8, v7
	v_div_scale_f32 v9, vcc, v214, v6, v214
	v_fma_f32 v10, -v7, v8, 1.0
	v_fmac_f32_e32 v8, v10, v8
	v_mul_f32_e32 v10, v9, v8
	v_fma_f32 v11, -v7, v10, v9
	v_fmac_f32_e32 v10, v11, v8
	v_fma_f32 v7, -v7, v10, v9
	v_div_fmas_f32 v7, v7, v8, v10
	v_div_fixup_f32 v214, v7, v6, v214
	ds_write_b32 v4, v214
	v_add_u32_e32 v4, 0x800, v4
	s_waitcnt vmcnt(8)
; __device__ __forceinline__ void prologue(const Args& a, LAS unsigned char* lds) {
;     ...
;         for (int i = tid; i < NB * DM; i += 512) { const float v = a.c[i]; sc[i] = v / (1.0f + __expf(-v)); }
	v_mul_f32_e32 v6, 0xbfb8aa3b, v215
	v_exp_f32_e32 v6, v6
	s_nop 0
	v_add_f32_e32 v6, 1.0, v6
	v_div_scale_f32 v7, s[12:13], v6, v6, v215
	v_rcp_f32_e32 v8, v7
	v_div_scale_f32 v9, vcc, v215, v6, v215
	v_fma_f32 v10, -v7, v8, 1.0
	v_fmac_f32_e32 v8, v10, v8
	v_mul_f32_e32 v10, v9, v8
	v_fma_f32 v11, -v7, v10, v9
	v_fmac_f32_e32 v10, v11, v8
	v_fma_f32 v7, -v7, v10, v9
	v_div_fmas_f32 v7, v7, v8, v10
	v_div_fixup_f32 v215, v7, v6, v215
	ds_write_b32 v4, v215
	v_add_u32_e32 v4, 0x800, v4
	s_waitcnt vmcnt(7)
	v_mul_f32_e32 v6, 0xbfb8aa3b, v216
	v_exp_f32_e32 v6, v6
	s_nop 0
	v_add_f32_e32 v6, 1.0, v6
	v_div_scale_f32 v7, s[12:13], v6, v6, v216
	v_rcp_f32_e32 v8, v7
	v_div_scale_f32 v9, vcc, v216, v6, v216
	v_fma_f32 v10, -v7, v8, 1.0
	v_fmac_f32_e32 v8, v10, v8
	v_mul_f32_e32 v10, v9, v8
	v_fma_f32 v11, -v7, v10, v9
	v_fmac_f32_e32 v10, v11, v8
	v_fma_f32 v7, -v7, v10, v9
	v_div_fmas_f32 v7, v7, v8, v10
	v_div_fixup_f32 v216, v7, v6, v216
	ds_write_b32 v4, v216
	v_add_u32_e32 v4, 0x800, v4
	s_waitcnt vmcnt(6)
	v_mul_f32_e32 v6, 0xbfb8aa3b, v217
	v_exp_f32_e32 v6, v6
	s_nop 0
	v_add_f32_e32 v6, 1.0, v6
	v_div_scale_f32 v7, s[12:13], v6, v6, v217
	v_rcp_f32_e32 v8, v7
	v_div_scale_f32 v9, vcc, v217, v6, v217
	v_fma_f32 v10, -v7, v8, 1.0
	v_fmac_f32_e32 v8, v10, v8
	v_mul_f32_e32 v10, v9, v8
	v_fma_f32 v11, -v7, v10, v9
	v_fmac_f32_e32 v10, v11, v8
	v_fma_f32 v7, -v7, v10, v9
	v_div_fmas_f32 v7, v7, v8, v10
	v_div_fixup_f32 v217, v7, v6, v217
	ds_write_b32 v4, v217
	v_add_u32_e32 v4, 0x800, v4
	s_waitcnt vmcnt(5)
	v_mul_f32_e32 v6, 0xbfb8aa3b, v218
	v_exp_f32_e32 v6, v6
	s_nop 0
	v_add_f32_e32 v6, 1.0, v6
	v_div_scale_f32 v7, s[12:13], v6, v6, v218
	v_rcp_f32_e32 v8, v7
	v_div_scale_f32 v9, vcc, v218, v6, v218
	v_fma_f32 v10, -v7, v8, 1.0
	v_fmac_f32_e32 v8, v10, v8
	v_mul_f32_e32 v10, v9, v8
	v_fma_f32 v11, -v7, v10, v9
	v_fmac_f32_e32 v10, v11, v8
	v_fma_f32 v7, -v7, v10, v9
	v_div_fmas_f32 v7, v7, v8, v10
	v_div_fixup_f32 v218, v7, v6, v218
	ds_write_b32 v4, v218
	v_add_u32_e32 v4, 0x800, v4
	s_waitcnt vmcnt(4)
	v_mul_f32_e32 v6, 0xbfb8aa3b, v219
	v_exp_f32_e32 v6, v6
	s_nop 0
	v_add_f32_e32 v6, 1.0, v6
	v_div_scale_f32 v7, s[12:13], v6, v6, v219
	v_rcp_f32_e32 v8, v7
	v_div_scale_f32 v9, vcc, v219, v6, v219
	v_fma_f32 v10, -v7, v8, 1.0
	v_fmac_f32_e32 v8, v10, v8
	v_mul_f32_e32 v10, v9, v8
	v_fma_f32 v11, -v7, v10, v9
	v_fmac_f32_e32 v10, v11, v8
	v_fma_f32 v7, -v7, v10, v9
	v_div_fmas_f32 v7, v7, v8, v10
	v_div_fixup_f32 v219, v7, v6, v219
	ds_write_b32 v4, v219
	v_add_u32_e32 v4, 0x800, v4
	s_waitcnt vmcnt(3)
	v_mul_f32_e32 v6, 0xbfb8aa3b, v220
	v_exp_f32_e32 v6, v6
	s_nop 0
	v_add_f32_e32 v6, 1.0, v6
	v_div_scale_f32 v7, s[12:13], v6, v6, v220
	v_rcp_f32_e32 v8, v7
	v_div_scale_f32 v9, vcc, v220, v6, v220
	v_fma_f32 v10, -v7, v8, 1.0
	v_fmac_f32_e32 v8, v10, v8
	v_mul_f32_e32 v10, v9, v8
	v_fma_f32 v11, -v7, v10, v9
	v_fmac_f32_e32 v10, v11, v8
	v_fma_f32 v7, -v7, v10, v9
	v_div_fmas_f32 v7, v7, v8, v10
	v_div_fixup_f32 v220, v7, v6, v220
	ds_write_b32 v4, v220
	v_add_u32_e32 v4, 0x800, v4
	s_waitcnt vmcnt(2)
	v_mul_f32_e32 v6, 0xbfb8aa3b, v221
	v_exp_f32_e32 v6, v6
	s_nop 0
	v_add_f32_e32 v6, 1.0, v6
	v_div_scale_f32 v7, s[12:13], v6, v6, v221
	v_rcp_f32_e32 v8, v7
	v_div_scale_f32 v9, vcc, v221, v6, v221
	v_fma_f32 v10, -v7, v8, 1.0
	v_fmac_f32_e32 v8, v10, v8
	v_mul_f32_e32 v10, v9, v8
	v_fma_f32 v11, -v7, v10, v9
	v_fmac_f32_e32 v10, v11, v8
	v_fma_f32 v7, -v7, v10, v9
	v_div_fmas_f32 v7, v7, v8, v10
	v_div_fixup_f32 v221, v7, v6, v221
	ds_write_b32 v4, v221
	v_add_u32_e32 v4, 0x800, v4
	s_waitcnt vmcnt(1)
	v_mul_f32_e32 v6, 0xbfb8aa3b, v222
	v_exp_f32_e32 v6, v6
	s_nop 0
	v_add_f32_e32 v6, 1.0, v6
	v_div_scale_f32 v7, s[12:13], v6, v6, v222
	v_rcp_f32_e32 v8, v7
	v_div_scale_f32 v9, vcc, v222, v6, v222
	v_fma_f32 v10, -v7, v8, 1.0
	v_fmac_f32_e32 v8, v10, v8
	v_mul_f32_e32 v10, v9, v8
	v_fma_f32 v11, -v7, v10, v9
	v_fmac_f32_e32 v10, v11, v8
	v_fma_f32 v7, -v7, v10, v9
	v_div_fmas_f32 v7, v7, v8, v10
	v_div_fixup_f32 v222, v7, v6, v222
	ds_write_b32 v4, v222
	v_add_u32_e32 v4, 0x800, v4
	s_waitcnt vmcnt(0)
	v_mul_f32_e32 v6, 0xbfb8aa3b, v223
	v_exp_f32_e32 v6, v6
	s_nop 0
	v_add_f32_e32 v6, 1.0, v6
	v_div_scale_f32 v7, s[12:13], v6, v6, v223
	v_rcp_f32_e32 v8, v7
	v_div_scale_f32 v9, vcc, v223, v6, v223
	v_fma_f32 v10, -v7, v8, 1.0
	v_fmac_f32_e32 v8, v10, v8
	v_mul_f32_e32 v10, v9, v8
	v_fma_f32 v11, -v7, v10, v9
	v_fmac_f32_e32 v10, v11, v8
	v_fma_f32 v7, -v7, v10, v9
	v_div_fmas_f32 v7, v7, v8, v10
	v_div_fixup_f32 v223, v7, v6, v223
	ds_write_b32 v4, v223
	v_add_u32_e32 v4, 0x800, v4
	v_add_u32_e32 v1, 0x2000, v1
	s_mov_b64 s[6:7], exec

; #define PG8_STAGE(bufoff, gbase, voff) do { _Pragma("unroll") for (int _i = 0; _i < 2; ++_i) \
;         __builtin_amdgcn_global_load_lds((const unsigned*)((const char*)(gbase) + (voff)[_i]), (PG8_LAS unsigned*)(lds + (bufoff) + ldsw + _i * 8192), 16, 0, 0); } while (0)
; #define PG8_WAIT_V(n) asm volatile("s_waitcnt vmcnt(" #n ")" ::: "memory")
;     __device__ __forceinline__ void operator()(const f32x4 (&acc)[2][2][4][2], const Unit& u, int wr, int wc, int fr, int fq) const {
;         const int row0 = u.pm * BM + wr * 64 + fr; int colt = u.pn * BM; bf16_t* base = O;
;         float sc = 1.f; if (split_cols) { const int t = colt / split_cols; base += (size_t)t * split_stride; colt -= t * split_cols; if (t == 0) sc = scale0; }
;         const int col0 = colt + wc * 32 + 8 * fq, bcol0 = u.pn * BM + wc * 32 + 8 * fq;
;     ...
;     for (int i = 0; i < 2; ++i) { int R, C; stage_rc(tid * 16 + i * 8192, R, C); const int Rb = Epi::PERM ? ((R & ~31) + perm32(R & 31)) : R;
;         voffA[i] = (unsigned)(R * K + C) * 2u; voffB[i] = (unsigned)(Rb * K + C) * 2u; }
;     const size_t kstep = (size_t)(BK * 2);
;     const size_t hstep = (size_t)HALF * K * 2;
;     const size_t tstep = 2 * hstep;
;     const unsigned ldsw = (unsigned)wid * 1024u;
;     const int aoff = lds_byte(wr * 64 + fr, fq * 8), boff = lds_byte(wc * 32 + fr, fq * 8);
;     ...
;     Unit cur, nxt; int ui = 0;
;     if (!S.next(0, cur)) return;
;     f32x4 acc[2][2][4][2];
; #pragma unroll
;     for (int a = 0; a < 2; ++a)
; #pragma unroll
;         for (int b = 0; b < 2; ++b)
; #pragma unroll
;             for (int m = 0; m < 4; ++m)
; #pragma unroll
;                 for (int n = 0; n < 2; ++n) acc[a][b][m][n] = (f32x4){0.f, 0.f, 0.f, 0.f};
;     bf16x8 At[4][2], B0[2][2], B1[2][2];
;     const char* cA = (const char*)g.A + (size_t)cur.pm * tstep; const char* cB = (const char*)g.Bt + (size_t)cur.pn * tstep;
;     S.a_ready(cur);
;     if constexpr (SP2) {
;         PG8_STAGE(PG8_SB(0, 0), cB, voffB); PG8_STAGE(PG8_SB(0, 1), cB + hstep, voffB); PG8_STAGEA(PG8_SA(0, 0), cA, voffA); PG8_STAGEA(PG8_SA(0, 1), cA + hstep, voffA);
;         if (wr == 1) PG8_BAR;
;         PG8_WAIT_V(2); PG8_BAR;
;         PG8_STAGE(PG8_SB(1, 0), cB + kstep, voffB); PG8_STAGEA(PG8_SA(1, 0), cA + kstep, voffA); PG8_STAGE(PG8_SB(1, 1), cB + hstep + kstep, voffB);
;         PG8_WAIT_V(6); PG8_BAR;
.LBB0_433:
	s_waitcnt vmcnt(0)
	v_lshrrev_b32_e32 v18, 1, v8
	v_and_b32_e32 v18, 24, v18
	v_and_b32_e32 v9, 15, v8
	v_lshlrev_b32_e32 v19, 1, v18
	v_lshlrev_b32_e32 v8, 2, v8
	s_lshl_b32 s17, s17, 5
	v_and_b32_e32 v248, 3, v192
	v_lshlrev_b32_e32 v248, 4, v248
	v_bfe_u32 v142, v192, 2, 4
	v_add_lshl_u32 v248, v248, v142, 2
	v_lshl_or_b32 v142, s36, 6, v142
	v_lshl_or_b32 v9, v9, 6, v19
	s_lshl_b32 s36, s36, 13
	v_and_b32_e32 v8, 32, v8
	s_and_b32 s17, s17, 0x60
	v_lshl_add_u64 v[10:11], s[50:51], 0, v[0:1]
	v_mov_b32_e32 v131, v1
	v_readlane_b32 s48, v245, 52
	v_bitop3_b32 v19, v9, s36, v8 bitop3:0xde
	s_lshl_b32 s36, s17, 7
	v_lshl_add_u64 v[12:13], s[50:51], 0, v[130:131]
	v_mov_b32_e32 v135, v1
	v_readlane_b32 s49, v245, 53
	v_bitop3_b32 v143, v9, s36, v8 bitop3:0xde
	s_add_i32 m0, s56, 0x18000
	v_lshl_add_u64 v[8:9], v[10:11], 0, s[8:9]
	v_lshl_add_u64 v[14:15], s[48:49], 0, v[134:135]
	v_mov_b32_e32 v133, v1
	s_waitcnt vmcnt(2)
	s_barrier
	global_load_lds_dwordx4 v[8:9], off
	v_lshl_add_u64 v[8:9], v[12:13], 0, s[8:9]
	s_add_i32 m0, s56, 0x1a000
	s_add_i32 s60, s56, 0x8000
	s_add_i32 s61, s56, 0xa000
	v_lshl_add_u64 v[16:17], s[48:49], 0, v[132:133]
	global_load_lds_dwordx4 v[8:9], off
	v_lshl_add_u64 v[8:9], v[14:15], 0, s[8:9]
	s_mov_b32 m0, s60
	s_add_u32 s36, s50, 0x40080
	global_load_lds_dwordx4 v[8:9], off
	v_lshl_add_u64 v[8:9], v[16:17], 0, s[8:9]
	s_mov_b32 m0, s61
	s_addc_u32 s37, s51, 0
	global_load_lds_dwordx4 v[8:9], off
	s_add_i32 m0, s56, 0x1c000
	v_lshl_add_u64 v[8:9], s[36:37], 0, v[0:1]
	global_load_lds_dwordx4 v[8:9], off
	v_lshl_add_u64 v[8:9], s[36:37], 0, v[130:131]
	s_add_i32 m0, s56, 0x1e000
	s_cmpk_lt_u32 s16, 0x100
	global_load_lds_dwordx4 v[8:9], off
	v_lshlrev_b32_e32 v8, 14, v6
	v_and_b32_e32 v8, 0xffff8000, v8
	v_lshl_add_u32 v5, v5, 11, v8
	v_and_b32_e32 v6, 1, v6
	v_lshl_or_b32 v5, v6, 6, v5
	v_lshl_add_u32 v136, v7, 1, v5
	v_lshlrev_b32_e32 v5, 14, v2
	v_and_b32_e32 v5, 0xffff8000, v5
	s_waitcnt vmcnt(6)
	v_lshl_add_u32 v3, v3, 11, v5
	v_and_b32_e32 v2, 1, v2
	v_and_b32_e32 v144, 3, v192
	v_lshlrev_b32_e32 v144, 3, v144
	v_or_b32_e32 v144, s17, v144
	v_lshl_or_b32 v2, v2, 6, v3
	v_readlane_b32 s16, v245, 48
	s_cselect_b64 s[36:37], -1, 0
	v_mov_b32_e32 v137, v1
	v_lshl_add_u32 v138, v4, 1, v2
	v_mov_b32_e32 v139, v1
	s_mov_b32 s62, 0
	v_add_u32_e32 v145, 0, v19
	v_readlane_b32 s63, v245, 47
	s_mov_b32 s64, s16
	s_barrier
	v_readlane_b32 s17, v245, 49
	s_branch .LBB0_436

; __device__ __forceinline__ unsigned cvt_pk_bf16(float lo, float hi) { unsigned r; asm volatile("v_cvt_pk_bf16_f32 %0, %1, %2" : "=v"(r) : "v"(lo), "v"(hi)); return r; }
;     __device__ __forceinline__ void operator()(const f32x4 (&acc)[2][2][4][2], const Unit& u, int wr, int wc, int fr, int fq) const {
;     ...
;             for (int m = 0; m < 4; ++m) { bf16_t* rowp = base + (size_t)(row0 + ai * HALF + m * 16) * ldc + col0;
; #pragma unroll
;                 for (int bj = 0; bj < 2; ++bj) { f32x4 v0 = acc[ai][bj][m][0] + bv[bj][0], v1 = acc[ai][bj][m][1] + bv[bj][1];
;                     if (ACT == 1) { f32x2 a = gelu_pk((f32x2){v0[0], v0[1]}), b = gelu_pk((f32x2){v0[2], v0[3]}), c = gelu_pk((f32x2){v1[0], v1[1]}), d = gelu_pk((f32x2){v1[2], v1[3]});
;                         v0 = (f32x4){a.x, a.y, b.x, b.y}; v1 = (f32x4){c.x, c.y, d.x, d.y}; }
;                     v0 = v0 * sc; v1 = v1 * sc; u32x4 w; w.x = cvt_pk_bf16(v0[0], v0[1]); w.y = cvt_pk_bf16(v0[2], v0[3]); w.z = cvt_pk_bf16(v1[0], v1[1]); w.w = cvt_pk_bf16(v1[2], v1[3]);
;                     *(u32x4*)(rowp + bj * HALF) = w; } }
.LBB0_446:
	v_lshl_add_u32 v146, s64, 8, v142
	v_lshl_or_b32 v140, s63, 8, v144
	v_ashrrev_i32_e32 v141, 31, v140
	v_ashrrev_i32_e32 v147, 31, v146
	v_lshl_add_u64 v[148:149], v[140:141], 1, s[82:83]
	v_lshlrev_b64 v[140:141], 11, v[146:147]
	v_lshl_add_u64 v[140:141], v[148:149], 0, v[140:141]
	v_pk_add_f32 v[128:129], v[128:129], 0 op_sel_hi:[1,0]
	v_pk_add_f32 v[126:127], v[126:127], 0 op_sel_hi:[1,0]
	v_pk_add_f32 v[150:151], v[124:125], 0 op_sel_hi:[1,0]
	v_pk_add_f32 v[124:125], v[122:123], 0 op_sel_hi:[1,0]
	v_cvt_pk_bf16_f32 v122, v126, v127
	v_cvt_pk_bf16_f32 v123, v128, v129
	v_pk_add_f32 v[118:119], v[118:119], 0 op_sel_hi:[1,0]
	v_cvt_pk_bf16_f32 v124, v124, v125
	v_cvt_pk_bf16_f32 v125, v150, v151
	ds_bpermute_b32 v122, v248, v122
	ds_bpermute_b32 v123, v248, v123
	ds_bpermute_b32 v124, v248, v124
	ds_bpermute_b32 v125, v248, v125
	s_waitcnt lgkmcnt(0)
	global_store_dwordx4 v[140:141], v[122:125], off
	v_pk_add_f32 v[120:121], v[120:121], 0 op_sel_hi:[1,0]
	v_pk_add_f32 v[114:115], v[114:115], 0 op_sel_hi:[1,0]
	v_pk_add_f32 v[122:123], v[112:113], 0 op_sel_hi:[1,0]
	v_pk_add_f32 v[112:113], v[110:111], 0 op_sel_hi:[1,0]
	v_cvt_pk_bf16_f32 v110, v118, v119
	v_cvt_pk_bf16_f32 v111, v120, v121
	v_pk_add_f32 v[102:103], v[102:103], 0 op_sel_hi:[1,0]
	v_cvt_pk_bf16_f32 v112, v112, v113
	v_cvt_pk_bf16_f32 v113, v122, v123
	ds_bpermute_b32 v110, v248, v110
	ds_bpermute_b32 v111, v248, v111
	ds_bpermute_b32 v112, v248, v112
	ds_bpermute_b32 v113, v248, v113
	s_waitcnt lgkmcnt(0)
	global_store_dwordx4 v[140:141], v[110:113], off offset:256
	v_pk_add_f32 v[104:105], v[104:105], 0 op_sel_hi:[1,0]
	v_pk_add_f32 v[98:99], v[98:99], 0 op_sel_hi:[1,0]
	v_or_b32_e32 v110, 16, v146
	v_ashrrev_i32_e32 v111, 31, v110
	v_lshlrev_b64 v[110:111], 11, v[110:111]
	v_lshl_add_u64 v[110:111], v[148:149], 0, v[110:111]
	v_pk_add_f32 v[112:113], v[116:117], 0 op_sel_hi:[1,0]
	v_pk_add_f32 v[116:117], v[108:109], 0 op_sel_hi:[1,0]
	v_pk_add_f32 v[108:109], v[106:107], 0 op_sel_hi:[1,0]
	v_cvt_pk_bf16_f32 v106, v114, v115
	v_cvt_pk_bf16_f32 v107, v112, v113
	v_pk_add_f32 v[86:87], v[86:87], 0 op_sel_hi:[1,0]
	v_cvt_pk_bf16_f32 v108, v108, v109
	v_cvt_pk_bf16_f32 v109, v116, v117
	ds_bpermute_b32 v106, v248, v106
	ds_bpermute_b32 v107, v248, v107
	ds_bpermute_b32 v108, v248, v108
	ds_bpermute_b32 v109, v248, v109
	s_waitcnt lgkmcnt(0)
	global_store_dwordx4 v[110:111], v[106:109], off
	v_pk_add_f32 v[88:89], v[88:89], 0 op_sel_hi:[1,0]
	v_pk_add_f32 v[82:83], v[82:83], 0 op_sel_hi:[1,0]
	v_pk_add_f32 v[106:107], v[96:97], 0 op_sel_hi:[1,0]
	v_pk_add_f32 v[96:97], v[94:95], 0 op_sel_hi:[1,0]
	v_cvt_pk_bf16_f32 v94, v102, v103
	v_cvt_pk_bf16_f32 v95, v104, v105
	v_pk_add_f32 v[72:73], v[72:73], 0 op_sel_hi:[1,0]
	v_cvt_pk_bf16_f32 v96, v96, v97
	v_cvt_pk_bf16_f32 v97, v106, v107
	ds_bpermute_b32 v94, v248, v94
	ds_bpermute_b32 v95, v248, v95
	ds_bpermute_b32 v96, v248, v96
	ds_bpermute_b32 v97, v248, v97
	s_waitcnt lgkmcnt(0)
	global_store_dwordx4 v[110:111], v[94:97], off offset:256
	v_pk_add_f32 v[70:71], v[70:71], 0 op_sel_hi:[1,0]
	s_mov_b64 s[16:17], 0x40000
	v_or_b32_e32 v94, 32, v146
	v_ashrrev_i32_e32 v95, 31, v94
	v_lshlrev_b64 v[94:95], 11, v[94:95]
	v_lshl_add_u64 v[94:95], v[148:149], 0, v[94:95]
	v_pk_add_f32 v[96:97], v[100:101], 0 op_sel_hi:[1,0]
	v_pk_add_f32 v[100:101], v[92:93], 0 op_sel_hi:[1,0]
	v_pk_add_f32 v[92:93], v[90:91], 0 op_sel_hi:[1,0]
	v_cvt_pk_bf16_f32 v90, v98, v99
	v_cvt_pk_bf16_f32 v91, v96, v97
	v_pk_add_f32 v[62:63], v[62:63], 0 op_sel_hi:[1,0]
	v_cvt_pk_bf16_f32 v92, v92, v93
	v_cvt_pk_bf16_f32 v93, v100, v101
	ds_bpermute_b32 v90, v248, v90
	ds_bpermute_b32 v91, v248, v91
	ds_bpermute_b32 v92, v248, v92
	ds_bpermute_b32 v93, v248, v93
	s_waitcnt lgkmcnt(0)
	global_store_dwordx4 v[94:95], v[90:93], off
	v_pk_add_f32 v[64:65], v[64:65], 0 op_sel_hi:[1,0]
	v_pk_add_f32 v[56:57], v[56:57], 0 op_sel_hi:[1,0]
	v_pk_add_f32 v[90:91], v[80:81], 0 op_sel_hi:[1,0]
	v_pk_add_f32 v[80:81], v[78:79], 0 op_sel_hi:[1,0]
	v_cvt_pk_bf16_f32 v78, v86, v87
	v_cvt_pk_bf16_f32 v79, v88, v89
	v_pk_add_f32 v[54:55], v[54:55], 0 op_sel_hi:[1,0]
	v_cvt_pk_bf16_f32 v80, v80, v81
	v_cvt_pk_bf16_f32 v81, v90, v91
	ds_bpermute_b32 v78, v248, v78
	ds_bpermute_b32 v79, v248, v79
	ds_bpermute_b32 v80, v248, v80
	ds_bpermute_b32 v81, v248, v81
	s_waitcnt lgkmcnt(0)
	global_store_dwordx4 v[94:95], v[78:81], off offset:256
	v_pk_add_f32 v[50:51], v[50:51], 0 op_sel_hi:[1,0]
	v_pk_add_f32 v[40:41], v[40:41], 0 op_sel_hi:[1,0]
	v_or_b32_e32 v78, 48, v146
	v_ashrrev_i32_e32 v79, 31, v78
	v_lshlrev_b64 v[78:79], 11, v[78:79]
	v_lshl_add_u64 v[78:79], v[148:149], 0, v[78:79]
	v_pk_add_f32 v[80:81], v[84:85], 0 op_sel_hi:[1,0]
	v_pk_add_f32 v[84:85], v[76:77], 0 op_sel_hi:[1,0]
	v_pk_add_f32 v[76:77], v[74:75], 0 op_sel_hi:[1,0]
	v_cvt_pk_bf16_f32 v74, v82, v83
	v_cvt_pk_bf16_f32 v75, v80, v81
	v_pk_add_f32 v[38:39], v[38:39], 0 op_sel_hi:[1,0]
	v_cvt_pk_bf16_f32 v76, v76, v77
	v_cvt_pk_bf16_f32 v77, v84, v85
	ds_bpermute_b32 v74, v248, v74
	ds_bpermute_b32 v75, v248, v75
	ds_bpermute_b32 v76, v248, v76
	ds_bpermute_b32 v77, v248, v77
	s_waitcnt lgkmcnt(0)
; __device__ __forceinline__ unsigned cvt_pk_bf16(float lo, float hi) { unsigned r; asm volatile("v_cvt_pk_bf16_f32 %0, %1, %2" : "=v"(r) : "v"(lo), "v"(hi)); return r; }
; #define PG8_BAR __builtin_amdgcn_s_barrier()
;     __device__ __forceinline__ void operator()(const f32x4 (&acc)[2][2][4][2], const Unit& u, int wr, int wc, int fr, int fq) const {
;     ...
;             for (int m = 0; m < 4; ++m) { bf16_t* rowp = base + (size_t)(row0 + ai * HALF + m * 16) * ldc + col0;
; #pragma unroll
;                 for (int bj = 0; bj < 2; ++bj) { f32x4 v0 = acc[ai][bj][m][0] + bv[bj][0], v1 = acc[ai][bj][m][1] + bv[bj][1];
;                     if (ACT == 1) { f32x2 a = gelu_pk((f32x2){v0[0], v0[1]}), b = gelu_pk((f32x2){v0[2], v0[3]}), c = gelu_pk((f32x2){v1[0], v1[1]}), d = gelu_pk((f32x2){v1[2], v1[3]});
;                         v0 = (f32x4){a.x, a.y, b.x, b.y}; v1 = (f32x4){c.x, c.y, d.x, d.y}; }
;                     v0 = v0 * sc; v1 = v1 * sc; u32x4 w; w.x = cvt_pk_bf16(v0[0], v0[1]); w.y = cvt_pk_bf16(v0[2], v0[3]); w.z = cvt_pk_bf16(v1[0], v1[1]); w.w = cvt_pk_bf16(v1[2], v1[3]);
;                     *(u32x4*)(rowp + bj * HALF) = w; } }
;     ...
;         if constexpr (ALIGN_EPI) { if (wr == 0) PG8_BAR; }
;         if constexpr (!Epi::AFTER_DRAIN) { E(acc, cur, wr, wc, fr, fq); S.done(cur); }
;         if (!has_next) break;
; #pragma unroll
;         for (int a = 0; a < 2; ++a)
; #pragma unroll
;             for (int b = 0; b < 2; ++b)
; #pragma unroll
;                 for (int m = 0; m < 4; ++m)
; #pragma unroll
;                     for (int n = 0; n < 2; ++n) acc[a][b][m][n] = (f32x4){0.f, 0.f, 0.f, 0.f};
;         cur = nxt; cA = nA; cB = nB; ++ui;
;         if constexpr (ALIGN_EPI) { if (wr == 1) PG8_BAR; }
	global_store_dwordx4 v[78:79], v[74:77], off
	v_pk_add_f32 v[34:35], v[34:35], 0 op_sel_hi:[1,0]
	v_pk_add_f32 v[24:25], v[24:25], 0 op_sel_hi:[1,0]
	v_pk_add_f32 v[74:75], v[68:69], 0 op_sel_hi:[1,0]
	v_pk_add_f32 v[68:69], v[66:67], 0 op_sel_hi:[1,0]
	v_cvt_pk_bf16_f32 v66, v70, v71
	v_cvt_pk_bf16_f32 v67, v72, v73
	v_pk_add_f32 v[22:23], v[22:23], 0 op_sel_hi:[1,0]
	v_cvt_pk_bf16_f32 v68, v68, v69
	v_cvt_pk_bf16_f32 v69, v74, v75
	ds_bpermute_b32 v66, v248, v66
	ds_bpermute_b32 v67, v248, v67
	ds_bpermute_b32 v68, v248, v68
	ds_bpermute_b32 v69, v248, v69
	s_waitcnt lgkmcnt(0)
	global_store_dwordx4 v[78:79], v[66:69], off offset:256
	v_pk_add_f32 v[18:19], v[18:19], 0 op_sel_hi:[1,0]
	v_pk_add_f32 v[8:9], v[8:9], 0 op_sel_hi:[1,0]
	v_lshl_add_u64 v[66:67], v[140:141], 0, s[16:17]
	s_mov_b32 s16, 0x40000
	v_pk_add_f32 v[68:69], v[60:61], 0 op_sel_hi:[1,0]
	v_pk_add_f32 v[60:61], v[58:59], 0 op_sel_hi:[1,0]
	v_cvt_pk_bf16_f32 v58, v62, v63
	v_add_co_u32_e32 v62, vcc, s16, v140
	v_cvt_pk_bf16_f32 v59, v64, v65
	v_cvt_pk_bf16_f32 v60, v60, v61
	v_cvt_pk_bf16_f32 v61, v68, v69
	s_mov_b64 s[16:17], 0x48000
	s_nop 0
	v_addc_co_u32_e32 v63, vcc, 0, v141, vcc
	ds_bpermute_b32 v58, v248, v58
	ds_bpermute_b32 v59, v248, v59
	ds_bpermute_b32 v60, v248, v60
	ds_bpermute_b32 v61, v248, v61
	s_waitcnt lgkmcnt(0)
	global_store_dwordx4 v[62:63], v[58:61], off
	v_pk_add_f32 v[6:7], v[6:7], 0 op_sel_hi:[1,0]
	s_nop 0
	v_pk_add_f32 v[58:59], v[48:49], 0 op_sel_hi:[1,0]
	v_pk_add_f32 v[48:49], v[46:47], 0 op_sel_hi:[1,0]
	v_cvt_pk_bf16_f32 v46, v54, v55
	v_cvt_pk_bf16_f32 v47, v56, v57
	s_nop 0
	v_cvt_pk_bf16_f32 v48, v48, v49
	v_cvt_pk_bf16_f32 v49, v58, v59
	ds_bpermute_b32 v46, v248, v46
	ds_bpermute_b32 v47, v248, v47
	ds_bpermute_b32 v48, v248, v48
	ds_bpermute_b32 v49, v248, v49
	s_waitcnt lgkmcnt(0)
	global_store_dwordx4 v[66:67], v[46:49], off offset:256
	s_nop 1
	v_lshl_add_u64 v[46:47], v[140:141], 0, s[16:17]
	v_pk_add_f32 v[48:49], v[52:53], 0 op_sel_hi:[1,0]
	s_mov_b32 s16, 0x48000
	v_pk_add_f32 v[52:53], v[44:45], 0 op_sel_hi:[1,0]
	v_pk_add_f32 v[44:45], v[42:43], 0 op_sel_hi:[1,0]
	v_cvt_pk_bf16_f32 v42, v50, v51
	v_cvt_pk_bf16_f32 v43, v48, v49
	v_add_co_u32_e32 v48, vcc, s16, v140
	v_cvt_pk_bf16_f32 v44, v44, v45
	v_cvt_pk_bf16_f32 v45, v52, v53
	s_mov_b64 s[16:17], 0x50000
	s_nop 0
	v_addc_co_u32_e32 v49, vcc, 0, v141, vcc
	ds_bpermute_b32 v42, v248, v42
	ds_bpermute_b32 v43, v248, v43
	ds_bpermute_b32 v44, v248, v44
	ds_bpermute_b32 v45, v248, v45
	s_waitcnt lgkmcnt(0)
	global_store_dwordx4 v[48:49], v[42:45], off
	s_nop 1
	v_pk_add_f32 v[42:43], v[32:33], 0 op_sel_hi:[1,0]
	v_pk_add_f32 v[32:33], v[30:31], 0 op_sel_hi:[1,0]
	v_cvt_pk_bf16_f32 v30, v38, v39
	v_cvt_pk_bf16_f32 v31, v40, v41
	s_nop 0
	v_cvt_pk_bf16_f32 v32, v32, v33
	v_cvt_pk_bf16_f32 v33, v42, v43
	ds_bpermute_b32 v30, v248, v30
	ds_bpermute_b32 v31, v248, v31
	ds_bpermute_b32 v32, v248, v32
	ds_bpermute_b32 v33, v248, v33
	s_waitcnt lgkmcnt(0)
	global_store_dwordx4 v[46:47], v[30:33], off offset:256
	s_nop 1
	v_lshl_add_u64 v[30:31], v[140:141], 0, s[16:17]
	v_pk_add_f32 v[32:33], v[36:37], 0 op_sel_hi:[1,0]
	s_mov_b32 s16, 0x50000
	v_pk_add_f32 v[36:37], v[28:29], 0 op_sel_hi:[1,0]
	v_pk_add_f32 v[28:29], v[26:27], 0 op_sel_hi:[1,0]
	v_cvt_pk_bf16_f32 v26, v34, v35
	v_cvt_pk_bf16_f32 v27, v32, v33
	v_add_co_u32_e32 v32, vcc, s16, v140
	v_cvt_pk_bf16_f32 v28, v28, v29
	v_cvt_pk_bf16_f32 v29, v36, v37
	s_mov_b64 s[16:17], 0x58000
	s_nop 0
	v_addc_co_u32_e32 v33, vcc, 0, v141, vcc
	ds_bpermute_b32 v26, v248, v26
	ds_bpermute_b32 v27, v248, v27
	ds_bpermute_b32 v28, v248, v28
	ds_bpermute_b32 v29, v248, v29
	s_waitcnt lgkmcnt(0)
	global_store_dwordx4 v[32:33], v[26:29], off
	s_nop 1
	v_pk_add_f32 v[26:27], v[16:17], 0 op_sel_hi:[1,0]
	v_pk_add_f32 v[16:17], v[14:15], 0 op_sel_hi:[1,0]
	v_cvt_pk_bf16_f32 v14, v22, v23
	v_cvt_pk_bf16_f32 v15, v24, v25
	s_nop 0
	v_cvt_pk_bf16_f32 v16, v16, v17
	v_cvt_pk_bf16_f32 v17, v26, v27
	ds_bpermute_b32 v14, v248, v14
	ds_bpermute_b32 v15, v248, v15
	ds_bpermute_b32 v16, v248, v16
	ds_bpermute_b32 v17, v248, v17
	s_waitcnt lgkmcnt(0)
	global_store_dwordx4 v[30:31], v[14:17], off offset:256
	s_nop 1
	v_lshl_add_u64 v[14:15], v[140:141], 0, s[16:17]
	v_pk_add_f32 v[16:17], v[20:21], 0 op_sel_hi:[1,0]
	s_mov_b32 s16, 0x58000
	v_pk_add_f32 v[20:21], v[12:13], 0 op_sel_hi:[1,0]
	v_pk_add_f32 v[12:13], v[10:11], 0 op_sel_hi:[1,0]
	v_cvt_pk_bf16_f32 v10, v18, v19
	v_cvt_pk_bf16_f32 v11, v16, v17
	v_add_co_u32_e32 v16, vcc, s16, v140
	v_cvt_pk_bf16_f32 v12, v12, v13
	v_cvt_pk_bf16_f32 v13, v20, v21
	s_mov_b64 s[16:17], -1
	s_nop 0
	v_addc_co_u32_e32 v17, vcc, 0, v141, vcc
	ds_bpermute_b32 v10, v248, v10
	ds_bpermute_b32 v11, v248, v11
	ds_bpermute_b32 v12, v248, v12
	ds_bpermute_b32 v13, v248, v13
	s_waitcnt lgkmcnt(0)
	global_store_dwordx4 v[16:17], v[10:13], off
	s_andn2_b64 vcc, exec, s[38:39]
	s_nop 0
	v_pk_add_f32 v[10:11], v[4:5], 0 op_sel_hi:[1,0]
	v_pk_add_f32 v[4:5], v[2:3], 0 op_sel_hi:[1,0]
	v_cvt_pk_bf16_f32 v2, v6, v7
	v_cvt_pk_bf16_f32 v3, v8, v9
	s_nop 0
	v_cvt_pk_bf16_f32 v4, v4, v5
	v_cvt_pk_bf16_f32 v5, v10, v11
	ds_bpermute_b32 v2, v248, v2
	ds_bpermute_b32 v3, v248, v3
	ds_bpermute_b32 v4, v248, v4
	ds_bpermute_b32 v5, v248, v5
	s_waitcnt lgkmcnt(0)
	global_store_dwordx4 v[14:15], v[2:5], off offset:256
	s_cbranch_vccnz .LBB0_435
	s_andn2_b64 vcc, exec, s[0:1]
	s_cbranch_vccnz .LBB0_434
	s_barrier
	s_branch .LBB0_434

; #define PG8_STAGE(bufoff, gbase, voff) do { _Pragma("unroll") for (int _i = 0; _i < 2; ++_i) \
;         __builtin_amdgcn_global_load_lds((const unsigned*)((const char*)(gbase) + (voff)[_i]), (PG8_LAS unsigned*)(lds + (bufoff) + ldsw + _i * 8192), 16, 0, 0); } while (0)
; #define PG8_WAIT_V(n) asm volatile("s_waitcnt vmcnt(" #n ")" ::: "memory")
;     __device__ __forceinline__ void operator()(const f32x4 (&acc)[2][2][4][2], const Unit& u, int wr, int wc, int fr, int fq) const {
;         const int row0 = u.pm * BM + wr * 64 + fr; int colt = u.pn * BM; bf16_t* base = O;
;         float sc = 1.f; if (split_cols) { const int t = colt / split_cols; base += (size_t)t * split_stride; colt -= t * split_cols; if (t == 0) sc = scale0; }
;         const int col0 = colt + wc * 32 + 8 * fq, bcol0 = u.pn * BM + wc * 32 + 8 * fq;
;     ...
;     for (int i = 0; i < 2; ++i) { int R, C; stage_rc(tid * 16 + i * 8192, R, C); const int Rb = Epi::PERM ? ((R & ~31) + perm32(R & 31)) : R;
;         voffA[i] = (unsigned)(R * K + C) * 2u; voffB[i] = (unsigned)(Rb * K + C) * 2u; }
;     const size_t kstep = (size_t)(BK * 2);
;     const size_t hstep = (size_t)HALF * K * 2;
;     const size_t tstep = 2 * hstep;
;     const unsigned ldsw = (unsigned)wid * 1024u;
;     const int aoff = lds_byte(wr * 64 + fr, fq * 8), boff = lds_byte(wc * 32 + fr, fq * 8);
;     ...
;     Unit cur, nxt; int ui = 0;
;     if (!S.next(0, cur)) return;
;     f32x4 acc[2][2][4][2];
; #pragma unroll
;     for (int a = 0; a < 2; ++a)
; #pragma unroll
;         for (int b = 0; b < 2; ++b)
; #pragma unroll
;             for (int m = 0; m < 4; ++m)
; #pragma unroll
;                 for (int n = 0; n < 2; ++n) acc[a][b][m][n] = (f32x4){0.f, 0.f, 0.f, 0.f};
;     bf16x8 At[4][2], B0[2][2], B1[2][2];
;     const char* cA = (const char*)g.A + (size_t)cur.pm * tstep; const char* cB = (const char*)g.Bt + (size_t)cur.pn * tstep;
;     S.a_ready(cur);
;     if constexpr (SP2) {
;         PG8_STAGE(PG8_SB(0, 0), cB, voffB); PG8_STAGE(PG8_SB(0, 1), cB + hstep, voffB); PG8_STAGEA(PG8_SA(0, 0), cA, voffA); PG8_STAGEA(PG8_SA(0, 1), cA + hstep, voffA);
;         if (wr == 1) PG8_BAR;
;         PG8_WAIT_V(2); PG8_BAR;
;         PG8_STAGE(PG8_SB(1, 0), cB + kstep, voffB); PG8_STAGEA(PG8_SA(1, 0), cA + kstep, voffA); PG8_STAGE(PG8_SB(1, 1), cB + hstep + kstep, voffB);
;         PG8_WAIT_V(6); PG8_BAR;
.LBB0_574:
	v_lshrrev_b32_e32 v18, 1, v8
	v_and_b32_e32 v18, 24, v18
	v_and_b32_e32 v9, 15, v8
	v_lshlrev_b32_e32 v19, 1, v18
	v_lshlrev_b32_e32 v8, 2, v8
	s_lshl_b32 s17, s17, 5
	v_and_b32_e32 v248, 3, v192
	v_lshlrev_b32_e32 v248, 4, v248
	v_bfe_u32 v142, v192, 2, 4
	v_add_lshl_u32 v248, v248, v142, 2
	v_lshl_or_b32 v142, s36, 6, v142
	v_lshl_or_b32 v9, v9, 6, v19
	s_lshl_b32 s36, s36, 13
	v_and_b32_e32 v8, 32, v8
	s_and_b32 s17, s17, 0x60
	v_lshl_add_u64 v[10:11], s[52:53], 0, v[0:1]
	v_mov_b32_e32 v131, v1
	v_readlane_b32 s50, v245, 61
	v_bitop3_b32 v19, v9, s36, v8 bitop3:0xde
	s_lshl_b32 s36, s17, 7
	v_lshl_add_u64 v[12:13], s[52:53], 0, v[130:131]
	v_mov_b32_e32 v135, v1
	v_readlane_b32 s51, v245, 62
	v_bitop3_b32 v143, v9, s36, v8 bitop3:0xde
	s_add_i32 m0, s58, 0x18000
	v_lshl_add_u64 v[8:9], v[10:11], 0, s[8:9]
	v_lshl_add_u64 v[14:15], s[50:51], 0, v[134:135]
	v_mov_b32_e32 v133, v1
	s_waitcnt vmcnt(2)
	s_barrier
	global_load_lds_dwordx4 v[8:9], off
	v_lshl_add_u64 v[8:9], v[12:13], 0, s[8:9]
	s_add_i32 m0, s58, 0x1a000
	s_add_i32 s62, s58, 0x8000
	s_add_i32 s63, s58, 0xa000
	v_lshl_add_u64 v[16:17], s[50:51], 0, v[132:133]
	global_load_lds_dwordx4 v[8:9], off
	v_lshl_add_u64 v[8:9], v[14:15], 0, s[8:9]
	s_mov_b32 m0, s62
	s_add_u32 s36, s52, 0x40080
	global_load_lds_dwordx4 v[8:9], off
	v_lshl_add_u64 v[8:9], v[16:17], 0, s[8:9]
	s_mov_b32 m0, s63
	s_addc_u32 s37, s53, 0
	global_load_lds_dwordx4 v[8:9], off
	s_add_i32 m0, s58, 0x1c000
	v_lshl_add_u64 v[8:9], s[36:37], 0, v[0:1]
	global_load_lds_dwordx4 v[8:9], off
	v_lshl_add_u64 v[8:9], s[36:37], 0, v[130:131]
	s_add_i32 m0, s58, 0x1e000
	s_cmpk_lt_u32 s16, 0x100
	global_load_lds_dwordx4 v[8:9], off
	v_lshlrev_b32_e32 v8, 14, v6
	v_and_b32_e32 v8, 0xffff8000, v8
	v_lshl_add_u32 v5, v5, 11, v8
	v_and_b32_e32 v6, 1, v6
	v_lshl_or_b32 v5, v6, 6, v5
	v_lshl_add_u32 v136, v7, 1, v5
	v_lshlrev_b32_e32 v5, 14, v2
	v_and_b32_e32 v5, 0xffff8000, v5
	s_waitcnt vmcnt(6)
	v_lshl_add_u32 v3, v3, 11, v5
	v_and_b32_e32 v2, 1, v2
	v_and_b32_e32 v144, 3, v192
	v_lshlrev_b32_e32 v144, 3, v144
	v_or_b32_e32 v144, s17, v144
	v_lshl_or_b32 v2, v2, 6, v3
	v_readlane_b32 s16, v245, 57
	s_cselect_b64 s[36:37], -1, 0
	v_mov_b32_e32 v137, v1
	v_lshl_add_u32 v138, v4, 1, v2
	v_mov_b32_e32 v139, v1
	s_mov_b32 s64, 0
	v_add_u32_e32 v145, 0, v19
	v_readlane_b32 s65, v245, 56
	s_mov_b32 s72, s16
	s_barrier
	v_readlane_b32 s17, v245, 58
	s_branch .LBB0_577

; __device__ __forceinline__ unsigned cvt_pk_bf16(float lo, float hi) { unsigned r; asm volatile("v_cvt_pk_bf16_f32 %0, %1, %2" : "=v"(r) : "v"(lo), "v"(hi)); return r; }
;     __device__ __forceinline__ void operator()(const f32x4 (&acc)[2][2][4][2], const Unit& u, int wr, int wc, int fr, int fq) const {
;     ...
;             for (int m = 0; m < 4; ++m) {
;                 bf16_t* rowp = O + (size_t)(row0 + ai * HALF + m * 16) * DFF + col0;
;                 f32x2 G[4], U[4], t[4], r[4];
; #pragma unroll
;                 for (int n = 0; n < 2; ++n) { G[2 * n] = (f32x2){acc[ai][0][m][n][0], acc[ai][0][m][n][1]}; G[2 * n + 1] = (f32x2){acc[ai][0][m][n][2], acc[ai][0][m][n][3]};
;                                               U[2 * n] = (f32x2){acc[ai][1][m][n][0], acc[ai][1][m][n][1]}; U[2 * n + 1] = (f32x2){acc[ai][1][m][n][2], acc[ai][1][m][n][3]}; }
; #pragma unroll
;                 for (int q = 0; q < 4; ++q) { t[q].x = __builtin_amdgcn_exp2f(G[q].x); t[q].y = __builtin_amdgcn_exp2f(G[q].y); }
; #pragma unroll
;                 for (int q = 0; q < 4; ++q) { t[q] = t[q] + 1.0f; r[q] = G[q] * U[q]; }
; #pragma unroll
;                 for (int q = 0; q < 4; ++q) { t[q].x = __builtin_amdgcn_rcpf(t[q].x); t[q].y = __builtin_amdgcn_rcpf(t[q].y); }
; #pragma unroll
;                 for (int q = 0; q < 4; ++q) r[q] = r[q] * t[q];
;                 u32x4 w; w.x = cvt_pk_bf16(r[0].x, r[0].y); w.y = cvt_pk_bf16(r[1].x, r[1].y); w.z = cvt_pk_bf16(r[2].x, r[2].y); w.w = cvt_pk_bf16(r[3].x, r[3].y);
;                 *(u32x4*)rowp = w;
.LBB0_583:
	v_exp_f32_e32 v152, v126
	v_exp_f32_e32 v153, v127
	v_exp_f32_e32 v156, v122
	v_exp_f32_e32 v157, v123
	v_exp_f32_e32 v154, v128
	v_exp_f32_e32 v155, v129
	v_exp_f32_e32 v158, v124
	v_exp_f32_e32 v159, v125
	v_pk_add_f32 v[152:153], v[152:153], 1.0 op_sel_hi:[1,0]
	v_pk_mul_f32 v[120:121], v[128:129], v[120:121]
	v_pk_add_f32 v[128:129], v[156:157], 1.0 op_sel_hi:[1,0]
	v_pk_mul_f32 v[118:119], v[126:127], v[118:119]
	v_pk_add_f32 v[126:127], v[154:155], 1.0 op_sel_hi:[1,0]
	v_pk_mul_f32 v[116:117], v[124:125], v[116:117]
	v_pk_mul_f32 v[114:115], v[122:123], v[114:115]
	v_pk_add_f32 v[122:123], v[158:159], 1.0 op_sel_hi:[1,0]
	v_rcp_f32_e32 v124, v152
	v_rcp_f32_e32 v125, v153
	v_rcp_f32_e32 v128, v128
	v_rcp_f32_e32 v129, v129
	v_rcp_f32_e32 v126, v126
	v_rcp_f32_e32 v127, v127
	v_rcp_f32_e32 v122, v122
	v_rcp_f32_e32 v123, v123
	v_lshl_or_b32 v148, s65, 7, v144
	v_lshl_add_u32 v146, s72, 8, v142
	v_ashrrev_i32_e32 v149, 31, v148
	v_mov_b64_e32 v[140:141], s[74:75]
	v_mad_i64_i32 v[150:151], s[16:17], v146, s87, v[140:141]
	v_pk_mul_f32 v[118:119], v[124:125], v[118:119]
	v_pk_mul_f32 v[124:125], v[128:129], v[114:115]
	v_lshlrev_b64 v[114:115], 1, v[148:149]
	v_pk_mul_f32 v[120:121], v[126:127], v[120:121]
	v_pk_mul_f32 v[122:123], v[122:123], v[116:117]
	v_lshl_add_u64 v[126:127], v[150:151], 0, v[114:115]
	v_cvt_pk_bf16_f32 v116, v118, v119
	v_cvt_pk_bf16_f32 v117, v120, v121
	v_cvt_pk_bf16_f32 v118, v124, v125
	v_cvt_pk_bf16_f32 v119, v122, v123
	ds_bpermute_b32 v116, v248, v116
	ds_bpermute_b32 v117, v248, v117
	ds_bpermute_b32 v118, v248, v118
	ds_bpermute_b32 v119, v248, v119
	s_waitcnt lgkmcnt(0)
	global_store_dwordx4 v[126:127], v[116:119], off
	v_exp_f32_e32 v120, v112
	v_exp_f32_e32 v121, v113
	v_exp_f32_e32 v118, v110
	v_exp_f32_e32 v119, v111
	v_exp_f32_e32 v122, v106
	v_exp_f32_e32 v123, v107
	v_exp_f32_e32 v124, v108
	v_exp_f32_e32 v125, v109
	v_pk_add_f32 v[118:119], v[118:119], 1.0 op_sel_hi:[1,0]
	v_pk_mul_f32 v[104:105], v[112:113], v[104:105]
	v_pk_mul_f32 v[102:103], v[110:111], v[102:103]
	v_pk_add_f32 v[110:111], v[120:121], 1.0 op_sel_hi:[1,0]
	v_pk_add_f32 v[112:113], v[122:123], 1.0 op_sel_hi:[1,0]
	v_pk_mul_f32 v[98:99], v[106:107], v[98:99]
	v_pk_add_f32 v[106:107], v[124:125], 1.0 op_sel_hi:[1,0]
	v_pk_mul_f32 v[100:101], v[108:109], v[100:101]
	v_rcp_f32_e32 v108, v118
	v_rcp_f32_e32 v109, v119
	v_rcp_f32_e32 v110, v110
	v_rcp_f32_e32 v111, v111
	v_rcp_f32_e32 v112, v112
	v_rcp_f32_e32 v113, v113
	v_rcp_f32_e32 v106, v106
	v_rcp_f32_e32 v107, v107
	v_or_b32_e32 v116, 16, v146
	v_mad_i64_i32 v[116:117], s[16:17], v116, s87, v[140:141]
	v_pk_mul_f32 v[102:103], v[108:109], v[102:103]
	v_pk_mul_f32 v[104:105], v[110:111], v[104:105]
	v_pk_mul_f32 v[108:109], v[112:113], v[98:99]
	v_pk_mul_f32 v[106:107], v[106:107], v[100:101]
	v_lshl_add_u64 v[110:111], v[116:117], 0, v[114:115]
	v_cvt_pk_bf16_f32 v98, v102, v103
	v_cvt_pk_bf16_f32 v99, v104, v105
	v_cvt_pk_bf16_f32 v100, v108, v109
	v_cvt_pk_bf16_f32 v101, v106, v107
	ds_bpermute_b32 v98, v248, v98
	ds_bpermute_b32 v99, v248, v99
	ds_bpermute_b32 v100, v248, v100
	ds_bpermute_b32 v101, v248, v101
	s_waitcnt lgkmcnt(0)
	global_store_dwordx4 v[110:111], v[98:101], off
	v_exp_f32_e32 v102, v96
	v_exp_f32_e32 v103, v97
	v_exp_f32_e32 v100, v94
	v_exp_f32_e32 v101, v95
	v_exp_f32_e32 v104, v90
	v_exp_f32_e32 v105, v91
	v_exp_f32_e32 v106, v92
	v_exp_f32_e32 v107, v93
	v_pk_add_f32 v[100:101], v[100:101], 1.0 op_sel_hi:[1,0]
	v_pk_mul_f32 v[88:89], v[96:97], v[88:89]
	v_pk_mul_f32 v[86:87], v[94:95], v[86:87]
	v_pk_add_f32 v[94:95], v[102:103], 1.0 op_sel_hi:[1,0]
	v_pk_add_f32 v[96:97], v[104:105], 1.0 op_sel_hi:[1,0]
	v_pk_mul_f32 v[82:83], v[90:91], v[82:83]
	v_pk_add_f32 v[90:91], v[106:107], 1.0 op_sel_hi:[1,0]
	v_pk_mul_f32 v[84:85], v[92:93], v[84:85]
	v_rcp_f32_e32 v92, v100
	v_rcp_f32_e32 v93, v101
	v_rcp_f32_e32 v94, v94
	v_rcp_f32_e32 v95, v95
	v_rcp_f32_e32 v96, v96
	v_rcp_f32_e32 v97, v97
	v_rcp_f32_e32 v90, v90
	v_rcp_f32_e32 v91, v91
	v_or_b32_e32 v98, 32, v146
	v_mad_i64_i32 v[98:99], s[16:17], v98, s87, v[140:141]
	v_pk_mul_f32 v[86:87], v[92:93], v[86:87]
	v_pk_mul_f32 v[88:89], v[94:95], v[88:89]
	v_pk_mul_f32 v[92:93], v[96:97], v[82:83]
	v_pk_mul_f32 v[90:91], v[90:91], v[84:85]
	v_lshl_add_u64 v[94:95], v[98:99], 0, v[114:115]
	v_cvt_pk_bf16_f32 v82, v86, v87
	v_cvt_pk_bf16_f32 v83, v88, v89
	v_cvt_pk_bf16_f32 v84, v92, v93
	v_cvt_pk_bf16_f32 v85, v90, v91
	ds_bpermute_b32 v82, v248, v82
	ds_bpermute_b32 v83, v248, v83
	ds_bpermute_b32 v84, v248, v84
	ds_bpermute_b32 v85, v248, v85
	s_waitcnt lgkmcnt(0)
	global_store_dwordx4 v[94:95], v[82:85], off
	v_exp_f32_e32 v86, v80
	v_exp_f32_e32 v87, v81
	v_exp_f32_e32 v84, v78
	v_exp_f32_e32 v85, v79
	v_exp_f32_e32 v88, v74
	v_exp_f32_e32 v89, v75
	v_exp_f32_e32 v90, v76
	v_exp_f32_e32 v91, v77
	v_pk_add_f32 v[84:85], v[84:85], 1.0 op_sel_hi:[1,0]
	v_pk_mul_f32 v[72:73], v[80:81], v[72:73]
	v_pk_mul_f32 v[70:71], v[78:79], v[70:71]
	v_pk_add_f32 v[78:79], v[86:87], 1.0 op_sel_hi:[1,0]
	v_pk_add_f32 v[80:81], v[88:89], 1.0 op_sel_hi:[1,0]
	v_pk_mul_f32 v[66:67], v[74:75], v[66:67]
	v_pk_add_f32 v[74:75], v[90:91], 1.0 op_sel_hi:[1,0]
	v_pk_mul_f32 v[68:69], v[76:77], v[68:69]
	v_rcp_f32_e32 v76, v84
	v_rcp_f32_e32 v77, v85
	v_rcp_f32_e32 v78, v78
	v_rcp_f32_e32 v79, v79
	v_rcp_f32_e32 v80, v80
	v_rcp_f32_e32 v81, v81
	v_rcp_f32_e32 v74, v74
	v_rcp_f32_e32 v75, v75
	v_or_b32_e32 v82, 48, v146
	v_mad_i64_i32 v[82:83], s[16:17], v82, s87, v[140:141]
	v_pk_mul_f32 v[70:71], v[76:77], v[70:71]
	v_pk_mul_f32 v[72:73], v[78:79], v[72:73]
	v_pk_mul_f32 v[76:77], v[80:81], v[66:67]
	v_pk_mul_f32 v[74:75], v[74:75], v[68:69]
	v_lshl_add_u64 v[78:79], v[82:83], 0, v[114:115]
	v_cvt_pk_bf16_f32 v66, v70, v71
	v_cvt_pk_bf16_f32 v67, v72, v73
	v_cvt_pk_bf16_f32 v68, v76, v77
	v_cvt_pk_bf16_f32 v69, v74, v75
	ds_bpermute_b32 v66, v248, v66
	ds_bpermute_b32 v67, v248, v67
	ds_bpermute_b32 v68, v248, v68
	ds_bpermute_b32 v69, v248, v69
	s_waitcnt lgkmcnt(0)
; __device__ __forceinline__ unsigned cvt_pk_bf16(float lo, float hi) { unsigned r; asm volatile("v_cvt_pk_bf16_f32 %0, %1, %2" : "=v"(r) : "v"(lo), "v"(hi)); return r; }
; #define PG8_BAR __builtin_amdgcn_s_barrier()
;     ...
;         if constexpr (ALIGN_EPI) { if (wr == 0) PG8_BAR; }
;         if constexpr (!Epi::AFTER_DRAIN) { E(acc, cur, wr, wc, fr, fq); S.done(cur); }
;         if (!has_next) break;
; #pragma unroll
;         for (int a = 0; a < 2; ++a)
; #pragma unroll
;             for (int b = 0; b < 2; ++b)
; #pragma unroll
;                 for (int m = 0; m < 4; ++m)
; #pragma unroll
;                     for (int n = 0; n < 2; ++n) acc[a][b][m][n] = (f32x4){0.f, 0.f, 0.f, 0.f};
;         cur = nxt; cA = nA; cB = nB; ++ui;
;         if constexpr (ALIGN_EPI) { if (wr == 1) PG8_BAR; }
;     __device__ __forceinline__ void operator()(const f32x4 (&acc)[2][2][4][2], const Unit& u, int wr, int wc, int fr, int fq) const {
;     ...
;             for (int m = 0; m < 4; ++m) {
;                 bf16_t* rowp = O + (size_t)(row0 + ai * HALF + m * 16) * DFF + col0;
;                 f32x2 G[4], U[4], t[4], r[4];
; #pragma unroll
;                 for (int n = 0; n < 2; ++n) { G[2 * n] = (f32x2){acc[ai][0][m][n][0], acc[ai][0][m][n][1]}; G[2 * n + 1] = (f32x2){acc[ai][0][m][n][2], acc[ai][0][m][n][3]};
;                                               U[2 * n] = (f32x2){acc[ai][1][m][n][0], acc[ai][1][m][n][1]}; U[2 * n + 1] = (f32x2){acc[ai][1][m][n][2], acc[ai][1][m][n][3]}; }
; #pragma unroll
;                 for (int q = 0; q < 4; ++q) { t[q].x = __builtin_amdgcn_exp2f(G[q].x); t[q].y = __builtin_amdgcn_exp2f(G[q].y); }
; #pragma unroll
;                 for (int q = 0; q < 4; ++q) { t[q] = t[q] + 1.0f; r[q] = G[q] * U[q]; }
; #pragma unroll
;                 for (int q = 0; q < 4; ++q) { t[q].x = __builtin_amdgcn_rcpf(t[q].x); t[q].y = __builtin_amdgcn_rcpf(t[q].y); }
; #pragma unroll
;                 for (int q = 0; q < 4; ++q) r[q] = r[q] * t[q];
;                 u32x4 w; w.x = cvt_pk_bf16(r[0].x, r[0].y); w.y = cvt_pk_bf16(r[1].x, r[1].y); w.z = cvt_pk_bf16(r[2].x, r[2].y); w.w = cvt_pk_bf16(r[3].x, r[3].y);
;                 *(u32x4*)rowp = w;
	global_store_dwordx4 v[78:79], v[66:69], off
	v_exp_f32_e32 v70, v64
	v_exp_f32_e32 v71, v65
	v_exp_f32_e32 v68, v62
	v_exp_f32_e32 v69, v63
	v_exp_f32_e32 v72, v58
	v_exp_f32_e32 v73, v59
	v_exp_f32_e32 v74, v60
	v_exp_f32_e32 v75, v61
	v_pk_add_f32 v[68:69], v[68:69], 1.0 op_sel_hi:[1,0]
	v_pk_mul_f32 v[56:57], v[64:65], v[56:57]
	v_pk_mul_f32 v[54:55], v[62:63], v[54:55]
	v_pk_add_f32 v[62:63], v[70:71], 1.0 op_sel_hi:[1,0]
	v_pk_add_f32 v[64:65], v[72:73], 1.0 op_sel_hi:[1,0]
	v_pk_mul_f32 v[50:51], v[58:59], v[50:51]
	v_pk_add_f32 v[58:59], v[74:75], 1.0 op_sel_hi:[1,0]
	v_pk_mul_f32 v[52:53], v[60:61], v[52:53]
	v_rcp_f32_e32 v60, v68
	v_rcp_f32_e32 v61, v69
	v_rcp_f32_e32 v62, v62
	v_rcp_f32_e32 v63, v63
	v_rcp_f32_e32 v64, v64
	v_rcp_f32_e32 v65, v65
	v_rcp_f32_e32 v58, v58
	v_rcp_f32_e32 v59, v59
	v_add_u32_e32 v66, 0x80, v146
	v_mad_i64_i32 v[66:67], s[16:17], v66, s87, v[140:141]
	v_pk_mul_f32 v[54:55], v[60:61], v[54:55]
	v_pk_mul_f32 v[56:57], v[62:63], v[56:57]
	v_pk_mul_f32 v[60:61], v[64:65], v[50:51]
	v_pk_mul_f32 v[58:59], v[58:59], v[52:53]
	v_lshl_add_u64 v[62:63], v[66:67], 0, v[114:115]
	v_cvt_pk_bf16_f32 v50, v54, v55
	v_cvt_pk_bf16_f32 v51, v56, v57
	v_cvt_pk_bf16_f32 v52, v60, v61
	v_cvt_pk_bf16_f32 v53, v58, v59
	ds_bpermute_b32 v50, v248, v50
	ds_bpermute_b32 v51, v248, v51
	ds_bpermute_b32 v52, v248, v52
	ds_bpermute_b32 v53, v248, v53
	s_waitcnt lgkmcnt(0)
	global_store_dwordx4 v[62:63], v[50:53], off
	v_exp_f32_e32 v54, v48
	v_exp_f32_e32 v55, v49
	v_exp_f32_e32 v52, v46
	v_exp_f32_e32 v53, v47
	v_exp_f32_e32 v56, v42
	v_exp_f32_e32 v57, v43
	v_exp_f32_e32 v58, v44
	v_exp_f32_e32 v59, v45
	v_pk_add_f32 v[52:53], v[52:53], 1.0 op_sel_hi:[1,0]
	v_pk_mul_f32 v[40:41], v[48:49], v[40:41]
	v_pk_mul_f32 v[38:39], v[46:47], v[38:39]
	v_pk_add_f32 v[46:47], v[54:55], 1.0 op_sel_hi:[1,0]
	v_pk_add_f32 v[48:49], v[56:57], 1.0 op_sel_hi:[1,0]
	v_pk_mul_f32 v[34:35], v[42:43], v[34:35]
	v_pk_add_f32 v[42:43], v[58:59], 1.0 op_sel_hi:[1,0]
	v_pk_mul_f32 v[36:37], v[44:45], v[36:37]
	v_rcp_f32_e32 v44, v52
	v_rcp_f32_e32 v45, v53
	v_rcp_f32_e32 v46, v46
	v_rcp_f32_e32 v47, v47
	v_rcp_f32_e32 v48, v48
	v_rcp_f32_e32 v49, v49
	v_rcp_f32_e32 v42, v42
	v_rcp_f32_e32 v43, v43
	v_add_u32_e32 v50, 0x90, v146
	v_mad_i64_i32 v[50:51], s[16:17], v50, s87, v[140:141]
	v_pk_mul_f32 v[38:39], v[44:45], v[38:39]
	v_pk_mul_f32 v[40:41], v[46:47], v[40:41]
	v_pk_mul_f32 v[44:45], v[48:49], v[34:35]
	v_pk_mul_f32 v[42:43], v[42:43], v[36:37]
	v_lshl_add_u64 v[46:47], v[50:51], 0, v[114:115]
	v_cvt_pk_bf16_f32 v34, v38, v39
	v_cvt_pk_bf16_f32 v35, v40, v41
	v_cvt_pk_bf16_f32 v36, v44, v45
	v_cvt_pk_bf16_f32 v37, v42, v43
	ds_bpermute_b32 v34, v248, v34
	ds_bpermute_b32 v35, v248, v35
	ds_bpermute_b32 v36, v248, v36
	ds_bpermute_b32 v37, v248, v37
	s_waitcnt lgkmcnt(0)
	global_store_dwordx4 v[46:47], v[34:37], off
	v_exp_f32_e32 v38, v32
	v_exp_f32_e32 v39, v33
	v_exp_f32_e32 v36, v30
	v_exp_f32_e32 v37, v31
	v_exp_f32_e32 v40, v26
	v_exp_f32_e32 v41, v27
	v_exp_f32_e32 v42, v28
	v_exp_f32_e32 v43, v29
	v_pk_add_f32 v[36:37], v[36:37], 1.0 op_sel_hi:[1,0]
	v_pk_mul_f32 v[24:25], v[32:33], v[24:25]
	v_pk_mul_f32 v[22:23], v[30:31], v[22:23]
	v_pk_add_f32 v[30:31], v[38:39], 1.0 op_sel_hi:[1,0]
	v_pk_add_f32 v[32:33], v[40:41], 1.0 op_sel_hi:[1,0]
	v_pk_mul_f32 v[20:21], v[28:29], v[20:21]
	v_pk_mul_f32 v[18:19], v[26:27], v[18:19]
	v_pk_add_f32 v[26:27], v[42:43], 1.0 op_sel_hi:[1,0]
	v_rcp_f32_e32 v28, v36
	v_rcp_f32_e32 v29, v37
	v_rcp_f32_e32 v30, v30
	v_rcp_f32_e32 v31, v31
	v_rcp_f32_e32 v32, v32
	v_rcp_f32_e32 v33, v33
	v_rcp_f32_e32 v26, v26
	v_rcp_f32_e32 v27, v27
	v_add_u32_e32 v34, 0xa0, v146
	v_mad_i64_i32 v[34:35], s[16:17], v34, s87, v[140:141]
	v_pk_mul_f32 v[22:23], v[28:29], v[22:23]
	v_pk_mul_f32 v[24:25], v[30:31], v[24:25]
	v_pk_mul_f32 v[28:29], v[32:33], v[18:19]
	v_pk_mul_f32 v[26:27], v[26:27], v[20:21]
	v_lshl_add_u64 v[30:31], v[34:35], 0, v[114:115]
	v_cvt_pk_bf16_f32 v18, v22, v23
	v_cvt_pk_bf16_f32 v19, v24, v25
	v_cvt_pk_bf16_f32 v20, v28, v29
	v_cvt_pk_bf16_f32 v21, v26, v27
	v_exp_f32_e32 v22, v16
	v_exp_f32_e32 v23, v17
	ds_bpermute_b32 v18, v248, v18
	ds_bpermute_b32 v19, v248, v19
	ds_bpermute_b32 v20, v248, v20
	ds_bpermute_b32 v21, v248, v21
	s_waitcnt lgkmcnt(0)
	global_store_dwordx4 v[30:31], v[18:21], off
	v_exp_f32_e32 v24, v10
	v_exp_f32_e32 v25, v11
	v_exp_f32_e32 v20, v14
	v_exp_f32_e32 v21, v15
	v_exp_f32_e32 v26, v12
	v_exp_f32_e32 v27, v13
	v_pk_mul_f32 v[6:7], v[14:15], v[6:7]
	v_pk_add_f32 v[14:15], v[22:23], 1.0 op_sel_hi:[1,0]
	v_pk_add_f32 v[20:21], v[20:21], 1.0 op_sel_hi:[1,0]
	v_pk_mul_f32 v[8:9], v[16:17], v[8:9]
	v_pk_add_f32 v[16:17], v[24:25], 1.0 op_sel_hi:[1,0]
	v_pk_mul_f32 v[2:3], v[10:11], v[2:3]
	v_pk_add_f32 v[10:11], v[26:27], 1.0 op_sel_hi:[1,0]
	v_rcp_f32_e32 v14, v14
	v_rcp_f32_e32 v15, v15
	v_pk_mul_f32 v[4:5], v[12:13], v[4:5]
	v_rcp_f32_e32 v12, v20
	v_rcp_f32_e32 v13, v21
	v_rcp_f32_e32 v16, v16
	v_rcp_f32_e32 v17, v17
	v_rcp_f32_e32 v10, v10
	v_rcp_f32_e32 v11, v11
	v_add_u32_e32 v18, 0xb0, v146
	v_mad_i64_i32 v[18:19], s[16:17], v18, s87, v[140:141]
	v_pk_mul_f32 v[8:9], v[14:15], v[8:9]
	v_lshl_add_u64 v[14:15], v[18:19], 0, v[114:115]
	s_andn2_b64 vcc, exec, s[40:41]
	s_mov_b64 s[16:17], -1
	v_pk_mul_f32 v[6:7], v[12:13], v[6:7]
	v_pk_mul_f32 v[12:13], v[16:17], v[2:3]
	v_pk_mul_f32 v[10:11], v[10:11], v[4:5]
	v_cvt_pk_bf16_f32 v2, v6, v7
	v_cvt_pk_bf16_f32 v3, v8, v9
	v_cvt_pk_bf16_f32 v4, v12, v13
	s_nop 0
	v_cvt_pk_bf16_f32 v5, v10, v11
	ds_bpermute_b32 v2, v248, v2
	ds_bpermute_b32 v3, v248, v3
	ds_bpermute_b32 v4, v248, v4
	ds_bpermute_b32 v5, v248, v5
	s_waitcnt lgkmcnt(0)
	global_store_dwordx4 v[14:15], v[2:5], off
	s_cbranch_vccnz .LBB0_576
	s_andn2_b64 vcc, exec, s[0:1]
	s_cbranch_vccnz .LBB0_575
	s_barrier
	s_branch .LBB0_575

; #define PG8_STAGE(bufoff, gbase, voff) do { _Pragma("unroll") for (int _i = 0; _i < 2; ++_i) \
;         __builtin_amdgcn_global_load_lds((const unsigned*)((const char*)(gbase) + (voff)[_i]), (PG8_LAS unsigned*)(lds + (bufoff) + ldsw + _i * 8192), 16, 0, 0); } while (0)
; #define PG8_WAIT_V(n) asm volatile("s_waitcnt vmcnt(" #n ")" ::: "memory")
;     __device__ __forceinline__ void operator()(const f32x4 (&acc)[2][2][4][2], const Unit& u, int wr, int wc, int fr, int fq) const {
;         const int row0 = u.pm * BM + wr * 64 + fr; int colt = u.pn * BM; bf16_t* base = O;
;         float sc = 1.f; if (split_cols) { const int t = colt / split_cols; base += (size_t)t * split_stride; colt -= t * split_cols; if (t == 0) sc = scale0; }
;         const int col0 = colt + wc * 32 + 8 * fq, bcol0 = u.pn * BM + wc * 32 + 8 * fq;
;     ...
;     for (int i = 0; i < 2; ++i) { int R, C; stage_rc(tid * 16 + i * 8192, R, C); const int Rb = Epi::PERM ? ((R & ~31) + perm32(R & 31)) : R;
;         voffA[i] = (unsigned)(R * K + C) * 2u; voffB[i] = (unsigned)(Rb * K + C) * 2u; }
;     const size_t kstep = (size_t)(BK * 2);
;     const size_t hstep = (size_t)HALF * K * 2;
;     const size_t tstep = 2 * hstep;
;     const unsigned ldsw = (unsigned)wid * 1024u;
;     const int aoff = lds_byte(wr * 64 + fr, fq * 8), boff = lds_byte(wc * 32 + fr, fq * 8);
;     ...
;     Unit cur, nxt; int ui = 0;
;     if (!S.next(0, cur)) return;
;     f32x4 acc[2][2][4][2];
; #pragma unroll
;     for (int a = 0; a < 2; ++a)
; #pragma unroll
;         for (int b = 0; b < 2; ++b)
; #pragma unroll
;             for (int m = 0; m < 4; ++m)
; #pragma unroll
;                 for (int n = 0; n < 2; ++n) acc[a][b][m][n] = (f32x4){0.f, 0.f, 0.f, 0.f};
;     bf16x8 At[4][2], B0[2][2], B1[2][2];
;     const char* cA = (const char*)g.A + (size_t)cur.pm * tstep; const char* cB = (const char*)g.Bt + (size_t)cur.pn * tstep;
;     S.a_ready(cur);
;     if constexpr (SP2) {
;         PG8_STAGE(PG8_SB(0, 0), cB, voffB); PG8_STAGE(PG8_SB(0, 1), cB + hstep, voffB); PG8_STAGEA(PG8_SA(0, 0), cA, voffA); PG8_STAGEA(PG8_SA(0, 1), cA + hstep, voffA);
;         if (wr == 1) PG8_BAR;
;         PG8_WAIT_V(2); PG8_BAR;
;         PG8_STAGE(PG8_SB(1, 0), cB + kstep, voffB); PG8_STAGEA(PG8_SA(1, 0), cA + kstep, voffA); PG8_STAGE(PG8_SB(1, 1), cB + hstep + kstep, voffB);
;         PG8_WAIT_V(6); PG8_BAR;
.LBB0_642:
	v_lshrrev_b32_e32 v20, 1, v14
	v_and_b32_e32 v20, 24, v20
	v_readlane_b32 s46, v244, 2
	v_and_b32_e32 v15, 15, v14
	v_lshlrev_b32_e32 v21, 1, v20
	v_lshlrev_b32_e32 v14, 2, v14
	s_lshl_b32 s1, s1, 5
	v_mov_b32_e32 v135, v1
	v_readlane_b32 s47, v244, 3
	v_and_b32_e32 v248, 3, v192
	v_lshlrev_b32_e32 v248, 4, v248
	v_bfe_u32 v142, v192, 2, 4
	v_add_lshl_u32 v248, v248, v142, 2
	v_lshl_or_b32 v142, s16, 6, v142
	v_lshl_or_b32 v15, v15, 6, v21
	s_lshl_b32 s16, s16, 13
	v_and_b32_e32 v14, 32, v14
	s_and_b32 s1, s1, 0x60
	s_add_i32 m0, s56, 0x18000
	v_lshl_add_u64 v[2:3], v[2:3], 0, s[8:9]
	v_lshl_add_u64 v[16:17], s[46:47], 0, v[134:135]
	v_mov_b32_e32 v133, v1
	v_bitop3_b32 v21, v15, s16, v14 bitop3:0xde
	s_lshl_b32 s16, s1, 7
	s_waitcnt vmcnt(2)
	s_barrier
	global_load_lds_dwordx4 v[2:3], off
	v_lshl_add_u64 v[2:3], v[4:5], 0, s[8:9]
	s_add_i32 m0, s56, 0x1a000
	s_add_i32 s60, s56, 0x8000
	s_add_i32 s61, s56, 0xa000
	v_lshl_add_u64 v[18:19], s[46:47], 0, v[132:133]
	v_bitop3_b32 v143, v15, s16, v14 bitop3:0xde
	global_load_lds_dwordx4 v[2:3], off
	v_lshl_add_u64 v[2:3], v[16:17], 0, s[8:9]
	s_mov_b32 m0, s60
	s_add_u32 s16, s48, 0xb0080
	global_load_lds_dwordx4 v[2:3], off
	v_lshl_add_u64 v[2:3], v[18:19], 0, s[8:9]
	s_mov_b32 m0, s61
	s_addc_u32 s17, s49, 0
	global_load_lds_dwordx4 v[2:3], off
	s_add_i32 m0, s56, 0x1c000
	v_lshl_add_u64 v[2:3], s[16:17], 0, v[0:1]
	global_load_lds_dwordx4 v[2:3], off
	v_lshl_add_u64 v[2:3], s[16:17], 0, v[130:131]
	s_add_i32 m0, s56, 0x1e000
	s_movk_i32 s16, 0xb00
	global_load_lds_dwordx4 v[2:3], off
	v_lshrrev_b32_e32 v3, 1, v11
	v_mul_lo_u32 v2, v10, s16
	s_mov_b32 s17, 0xb000
	s_cmpk_lt_u32 s0, 0x100
	v_and_b32_e32 v144, 3, v192
	v_lshlrev_b32_e32 v144, 3, v144
	v_or_b32_e32 v144, s1, v144
	v_mad_u64_u32 v[2:3], s[0:1], v3, s17, v[2:3]
	v_or_b32_e32 v2, v2, v12
	v_add_lshl_u32 v2, v2, v13, 1
	v_mov_b32_e32 v3, v1
	s_mov_b64 s[36:37], 0xb0080
	v_lshl_add_u64 v[136:137], v[2:3], 0, s[36:37]
	v_lshrrev_b32_e32 v3, 1, v6
	v_mul_lo_u32 v2, v7, s16
	v_mad_u64_u32 v[2:3], s[0:1], v3, s17, v[2:3]
	s_waitcnt vmcnt(6)
	v_or_b32_e32 v2, v2, v8
	v_add_lshl_u32 v2, v2, v9, 1
	v_mov_b32_e32 v3, v1
	s_cselect_b64 s[42:43], -1, 0
	v_lshl_add_u64 v[138:139], v[2:3], 0, s[36:37]
	s_mov_b32 s62, 0
	v_add_u32_e32 v145, 0, v21
	v_readlane_b32 s65, v245, 47
	v_readlane_b32 s72, v244, 1
	s_barrier
	s_branch .LBB0_645

; __device__ __forceinline__ unsigned cvt_pk_bf16(float lo, float hi) { unsigned r; asm volatile("v_cvt_pk_bf16_f32 %0, %1, %2" : "=v"(r) : "v"(lo), "v"(hi)); return r; }
;     __device__ __forceinline__ void operator()(const f32x4 (&acc)[2][2][4][2], const Unit& u, int wr, int wc, int fr, int fq) const {
;     ...
;             for (int m = 0; m < 4; ++m) { bf16_t* rowp = base + (size_t)(row0 + ai * HALF + m * 16) * ldc + col0;
; #pragma unroll
;                 for (int bj = 0; bj < 2; ++bj) { f32x4 v0 = acc[ai][bj][m][0] + bv[bj][0], v1 = acc[ai][bj][m][1] + bv[bj][1];
;                     if (ACT == 1) { f32x2 a = gelu_pk((f32x2){v0[0], v0[1]}), b = gelu_pk((f32x2){v0[2], v0[3]}), c = gelu_pk((f32x2){v1[0], v1[1]}), d = gelu_pk((f32x2){v1[2], v1[3]});
;                         v0 = (f32x4){a.x, a.y, b.x, b.y}; v1 = (f32x4){c.x, c.y, d.x, d.y}; }
;                     v0 = v0 * sc; v1 = v1 * sc; u32x4 w; w.x = cvt_pk_bf16(v0[0], v0[1]); w.y = cvt_pk_bf16(v0[2], v0[3]); w.z = cvt_pk_bf16(v1[0], v1[1]); w.w = cvt_pk_bf16(v1[2], v1[3]);
;                     *(u32x4*)(rowp + bj * HALF) = w; } }
.LBB0_659:
	v_lshl_add_u32 v146, s72, 8, v142
	v_lshl_or_b32 v140, s65, 8, v144
	v_ashrrev_i32_e32 v141, 31, v140
	v_ashrrev_i32_e32 v147, 31, v146
	v_lshl_add_u64 v[148:149], v[140:141], 1, s[82:83]
	v_lshlrev_b64 v[140:141], 11, v[146:147]
	v_lshl_add_u64 v[140:141], v[148:149], 0, v[140:141]
	v_pk_add_f32 v[128:129], v[128:129], 0 op_sel_hi:[1,0]
	v_pk_add_f32 v[126:127], v[126:127], 0 op_sel_hi:[1,0]
	v_pk_add_f32 v[150:151], v[124:125], 0 op_sel_hi:[1,0]
	v_pk_add_f32 v[124:125], v[122:123], 0 op_sel_hi:[1,0]
	v_cvt_pk_bf16_f32 v122, v126, v127
	v_cvt_pk_bf16_f32 v123, v128, v129
	v_pk_add_f32 v[118:119], v[118:119], 0 op_sel_hi:[1,0]
	v_cvt_pk_bf16_f32 v124, v124, v125
	v_cvt_pk_bf16_f32 v125, v150, v151
	ds_bpermute_b32 v122, v248, v122
	ds_bpermute_b32 v123, v248, v123
	ds_bpermute_b32 v124, v248, v124
	ds_bpermute_b32 v125, v248, v125
	s_waitcnt lgkmcnt(0)
	global_store_dwordx4 v[140:141], v[122:125], off
	v_pk_add_f32 v[120:121], v[120:121], 0 op_sel_hi:[1,0]
	v_pk_add_f32 v[114:115], v[114:115], 0 op_sel_hi:[1,0]
	v_pk_add_f32 v[122:123], v[112:113], 0 op_sel_hi:[1,0]
	v_pk_add_f32 v[112:113], v[110:111], 0 op_sel_hi:[1,0]
	v_cvt_pk_bf16_f32 v110, v118, v119
	v_cvt_pk_bf16_f32 v111, v120, v121
	v_pk_add_f32 v[102:103], v[102:103], 0 op_sel_hi:[1,0]
	v_cvt_pk_bf16_f32 v112, v112, v113
	v_cvt_pk_bf16_f32 v113, v122, v123
	ds_bpermute_b32 v110, v248, v110
	ds_bpermute_b32 v111, v248, v111
	ds_bpermute_b32 v112, v248, v112
	ds_bpermute_b32 v113, v248, v113
	s_waitcnt lgkmcnt(0)
	global_store_dwordx4 v[140:141], v[110:113], off offset:256
	v_pk_add_f32 v[104:105], v[104:105], 0 op_sel_hi:[1,0]
	v_pk_add_f32 v[98:99], v[98:99], 0 op_sel_hi:[1,0]
	v_or_b32_e32 v110, 16, v146
	v_ashrrev_i32_e32 v111, 31, v110
	v_lshlrev_b64 v[110:111], 11, v[110:111]
	v_lshl_add_u64 v[110:111], v[148:149], 0, v[110:111]
	v_pk_add_f32 v[112:113], v[116:117], 0 op_sel_hi:[1,0]
	v_pk_add_f32 v[116:117], v[108:109], 0 op_sel_hi:[1,0]
	v_pk_add_f32 v[108:109], v[106:107], 0 op_sel_hi:[1,0]
	v_cvt_pk_bf16_f32 v106, v114, v115
	v_cvt_pk_bf16_f32 v107, v112, v113
	v_pk_add_f32 v[86:87], v[86:87], 0 op_sel_hi:[1,0]
	v_cvt_pk_bf16_f32 v108, v108, v109
	v_cvt_pk_bf16_f32 v109, v116, v117
	ds_bpermute_b32 v106, v248, v106
	ds_bpermute_b32 v107, v248, v107
	ds_bpermute_b32 v108, v248, v108
	ds_bpermute_b32 v109, v248, v109
	s_waitcnt lgkmcnt(0)
	global_store_dwordx4 v[110:111], v[106:109], off
	v_pk_add_f32 v[88:89], v[88:89], 0 op_sel_hi:[1,0]
	v_pk_add_f32 v[82:83], v[82:83], 0 op_sel_hi:[1,0]
	v_pk_add_f32 v[106:107], v[96:97], 0 op_sel_hi:[1,0]
	v_pk_add_f32 v[96:97], v[94:95], 0 op_sel_hi:[1,0]
	v_cvt_pk_bf16_f32 v94, v102, v103
	v_cvt_pk_bf16_f32 v95, v104, v105
	v_pk_add_f32 v[72:73], v[72:73], 0 op_sel_hi:[1,0]
	v_cvt_pk_bf16_f32 v96, v96, v97
	v_cvt_pk_bf16_f32 v97, v106, v107
	ds_bpermute_b32 v94, v248, v94
	ds_bpermute_b32 v95, v248, v95
	ds_bpermute_b32 v96, v248, v96
	ds_bpermute_b32 v97, v248, v97
	s_waitcnt lgkmcnt(0)
	global_store_dwordx4 v[110:111], v[94:97], off offset:256
	v_pk_add_f32 v[70:71], v[70:71], 0 op_sel_hi:[1,0]
	s_mov_b64 s[16:17], 0x40000
	v_or_b32_e32 v94, 32, v146
	v_ashrrev_i32_e32 v95, 31, v94
	v_lshlrev_b64 v[94:95], 11, v[94:95]
	v_lshl_add_u64 v[94:95], v[148:149], 0, v[94:95]
	v_pk_add_f32 v[96:97], v[100:101], 0 op_sel_hi:[1,0]
	v_pk_add_f32 v[100:101], v[92:93], 0 op_sel_hi:[1,0]
	v_pk_add_f32 v[92:93], v[90:91], 0 op_sel_hi:[1,0]
	v_cvt_pk_bf16_f32 v90, v98, v99
	v_cvt_pk_bf16_f32 v91, v96, v97
	v_pk_add_f32 v[62:63], v[62:63], 0 op_sel_hi:[1,0]
	v_cvt_pk_bf16_f32 v92, v92, v93
	v_cvt_pk_bf16_f32 v93, v100, v101
	ds_bpermute_b32 v90, v248, v90
	ds_bpermute_b32 v91, v248, v91
	ds_bpermute_b32 v92, v248, v92
	ds_bpermute_b32 v93, v248, v93
	s_waitcnt lgkmcnt(0)
	global_store_dwordx4 v[94:95], v[90:93], off
	v_pk_add_f32 v[64:65], v[64:65], 0 op_sel_hi:[1,0]
	v_pk_add_f32 v[56:57], v[56:57], 0 op_sel_hi:[1,0]
	v_pk_add_f32 v[90:91], v[80:81], 0 op_sel_hi:[1,0]
	v_pk_add_f32 v[80:81], v[78:79], 0 op_sel_hi:[1,0]
	v_cvt_pk_bf16_f32 v78, v86, v87
	v_cvt_pk_bf16_f32 v79, v88, v89
	v_pk_add_f32 v[54:55], v[54:55], 0 op_sel_hi:[1,0]
	v_cvt_pk_bf16_f32 v80, v80, v81
	v_cvt_pk_bf16_f32 v81, v90, v91
	ds_bpermute_b32 v78, v248, v78
	ds_bpermute_b32 v79, v248, v79
	ds_bpermute_b32 v80, v248, v80
	ds_bpermute_b32 v81, v248, v81
	s_waitcnt lgkmcnt(0)
	global_store_dwordx4 v[94:95], v[78:81], off offset:256
	v_pk_add_f32 v[50:51], v[50:51], 0 op_sel_hi:[1,0]
	v_pk_add_f32 v[40:41], v[40:41], 0 op_sel_hi:[1,0]
	v_or_b32_e32 v78, 48, v146
	v_ashrrev_i32_e32 v79, 31, v78
	v_lshlrev_b64 v[78:79], 11, v[78:79]
	v_lshl_add_u64 v[78:79], v[148:149], 0, v[78:79]
	v_pk_add_f32 v[80:81], v[84:85], 0 op_sel_hi:[1,0]
	v_pk_add_f32 v[84:85], v[76:77], 0 op_sel_hi:[1,0]
	v_pk_add_f32 v[76:77], v[74:75], 0 op_sel_hi:[1,0]
	v_cvt_pk_bf16_f32 v74, v82, v83
	v_cvt_pk_bf16_f32 v75, v80, v81
	v_pk_add_f32 v[38:39], v[38:39], 0 op_sel_hi:[1,0]
	v_cvt_pk_bf16_f32 v76, v76, v77
	v_cvt_pk_bf16_f32 v77, v84, v85
	ds_bpermute_b32 v74, v248, v74
	ds_bpermute_b32 v75, v248, v75
	ds_bpermute_b32 v76, v248, v76
	ds_bpermute_b32 v77, v248, v77
	s_waitcnt lgkmcnt(0)
; __device__ __forceinline__ unsigned cvt_pk_bf16(float lo, float hi) { unsigned r; asm volatile("v_cvt_pk_bf16_f32 %0, %1, %2" : "=v"(r) : "v"(lo), "v"(hi)); return r; }
; #define PG8_BAR __builtin_amdgcn_s_barrier()
;     __device__ __forceinline__ void operator()(const f32x4 (&acc)[2][2][4][2], const Unit& u, int wr, int wc, int fr, int fq) const {
;     ...
;             for (int m = 0; m < 4; ++m) { bf16_t* rowp = base + (size_t)(row0 + ai * HALF + m * 16) * ldc + col0;
; #pragma unroll
;                 for (int bj = 0; bj < 2; ++bj) { f32x4 v0 = acc[ai][bj][m][0] + bv[bj][0], v1 = acc[ai][bj][m][1] + bv[bj][1];
;                     if (ACT == 1) { f32x2 a = gelu_pk((f32x2){v0[0], v0[1]}), b = gelu_pk((f32x2){v0[2], v0[3]}), c = gelu_pk((f32x2){v1[0], v1[1]}), d = gelu_pk((f32x2){v1[2], v1[3]});
;                         v0 = (f32x4){a.x, a.y, b.x, b.y}; v1 = (f32x4){c.x, c.y, d.x, d.y}; }
;                     v0 = v0 * sc; v1 = v1 * sc; u32x4 w; w.x = cvt_pk_bf16(v0[0], v0[1]); w.y = cvt_pk_bf16(v0[2], v0[3]); w.z = cvt_pk_bf16(v1[0], v1[1]); w.w = cvt_pk_bf16(v1[2], v1[3]);
;                     *(u32x4*)(rowp + bj * HALF) = w; } }
;     ...
;         if constexpr (ALIGN_EPI) { if (wr == 0) PG8_BAR; }
;         if constexpr (!Epi::AFTER_DRAIN) { E(acc, cur, wr, wc, fr, fq); S.done(cur); }
;         if (!has_next) break;
; #pragma unroll
;         for (int a = 0; a < 2; ++a)
; #pragma unroll
;             for (int b = 0; b < 2; ++b)
; #pragma unroll
;                 for (int m = 0; m < 4; ++m)
; #pragma unroll
;                     for (int n = 0; n < 2; ++n) acc[a][b][m][n] = (f32x4){0.f, 0.f, 0.f, 0.f};
;         cur = nxt; cA = nA; cB = nB; ++ui;
;         if constexpr (ALIGN_EPI) { if (wr == 1) PG8_BAR; }
	global_store_dwordx4 v[78:79], v[74:77], off
	v_pk_add_f32 v[34:35], v[34:35], 0 op_sel_hi:[1,0]
	v_pk_add_f32 v[24:25], v[24:25], 0 op_sel_hi:[1,0]
	v_pk_add_f32 v[74:75], v[68:69], 0 op_sel_hi:[1,0]
	v_pk_add_f32 v[68:69], v[66:67], 0 op_sel_hi:[1,0]
	v_cvt_pk_bf16_f32 v66, v70, v71
	v_cvt_pk_bf16_f32 v67, v72, v73
	v_pk_add_f32 v[22:23], v[22:23], 0 op_sel_hi:[1,0]
	v_cvt_pk_bf16_f32 v68, v68, v69
	v_cvt_pk_bf16_f32 v69, v74, v75
	ds_bpermute_b32 v66, v248, v66
	ds_bpermute_b32 v67, v248, v67
	ds_bpermute_b32 v68, v248, v68
	ds_bpermute_b32 v69, v248, v69
	s_waitcnt lgkmcnt(0)
	global_store_dwordx4 v[78:79], v[66:69], off offset:256
	v_pk_add_f32 v[18:19], v[18:19], 0 op_sel_hi:[1,0]
	v_pk_add_f32 v[8:9], v[8:9], 0 op_sel_hi:[1,0]
	v_lshl_add_u64 v[66:67], v[140:141], 0, s[16:17]
	s_mov_b32 s16, 0x40000
	v_pk_add_f32 v[68:69], v[60:61], 0 op_sel_hi:[1,0]
	v_pk_add_f32 v[60:61], v[58:59], 0 op_sel_hi:[1,0]
	v_cvt_pk_bf16_f32 v58, v62, v63
	v_add_co_u32_e32 v62, vcc, s16, v140
	v_cvt_pk_bf16_f32 v59, v64, v65
	v_cvt_pk_bf16_f32 v60, v60, v61
	v_cvt_pk_bf16_f32 v61, v68, v69
	s_mov_b64 s[16:17], 0x48000
	s_nop 0
	v_addc_co_u32_e32 v63, vcc, 0, v141, vcc
	ds_bpermute_b32 v58, v248, v58
	ds_bpermute_b32 v59, v248, v59
	ds_bpermute_b32 v60, v248, v60
	ds_bpermute_b32 v61, v248, v61
	s_waitcnt lgkmcnt(0)
	global_store_dwordx4 v[62:63], v[58:61], off
	v_pk_add_f32 v[6:7], v[6:7], 0 op_sel_hi:[1,0]
	s_nop 0
	v_pk_add_f32 v[58:59], v[48:49], 0 op_sel_hi:[1,0]
	v_pk_add_f32 v[48:49], v[46:47], 0 op_sel_hi:[1,0]
	v_cvt_pk_bf16_f32 v46, v54, v55
	v_cvt_pk_bf16_f32 v47, v56, v57
	s_nop 0
	v_cvt_pk_bf16_f32 v48, v48, v49
	v_cvt_pk_bf16_f32 v49, v58, v59
	ds_bpermute_b32 v46, v248, v46
	ds_bpermute_b32 v47, v248, v47
	ds_bpermute_b32 v48, v248, v48
	ds_bpermute_b32 v49, v248, v49
	s_waitcnt lgkmcnt(0)
	global_store_dwordx4 v[66:67], v[46:49], off offset:256
	s_nop 1
	v_lshl_add_u64 v[46:47], v[140:141], 0, s[16:17]
	v_pk_add_f32 v[48:49], v[52:53], 0 op_sel_hi:[1,0]
	s_mov_b32 s16, 0x48000
	v_pk_add_f32 v[52:53], v[44:45], 0 op_sel_hi:[1,0]
	v_pk_add_f32 v[44:45], v[42:43], 0 op_sel_hi:[1,0]
	v_cvt_pk_bf16_f32 v42, v50, v51
	v_cvt_pk_bf16_f32 v43, v48, v49
	v_add_co_u32_e32 v48, vcc, s16, v140
	v_cvt_pk_bf16_f32 v44, v44, v45
	v_cvt_pk_bf16_f32 v45, v52, v53
	s_mov_b64 s[16:17], 0x50000
	s_nop 0
	v_addc_co_u32_e32 v49, vcc, 0, v141, vcc
	ds_bpermute_b32 v42, v248, v42
	ds_bpermute_b32 v43, v248, v43
	ds_bpermute_b32 v44, v248, v44
	ds_bpermute_b32 v45, v248, v45
	s_waitcnt lgkmcnt(0)
	global_store_dwordx4 v[48:49], v[42:45], off
	s_nop 1
	v_pk_add_f32 v[42:43], v[32:33], 0 op_sel_hi:[1,0]
	v_pk_add_f32 v[32:33], v[30:31], 0 op_sel_hi:[1,0]
	v_cvt_pk_bf16_f32 v30, v38, v39
	v_cvt_pk_bf16_f32 v31, v40, v41
	s_nop 0
	v_cvt_pk_bf16_f32 v32, v32, v33
	v_cvt_pk_bf16_f32 v33, v42, v43
	ds_bpermute_b32 v30, v248, v30
	ds_bpermute_b32 v31, v248, v31
	ds_bpermute_b32 v32, v248, v32
	ds_bpermute_b32 v33, v248, v33
	s_waitcnt lgkmcnt(0)
	global_store_dwordx4 v[46:47], v[30:33], off offset:256
	s_nop 1
	v_lshl_add_u64 v[30:31], v[140:141], 0, s[16:17]
	v_pk_add_f32 v[32:33], v[36:37], 0 op_sel_hi:[1,0]
	s_mov_b32 s16, 0x50000
	v_pk_add_f32 v[36:37], v[28:29], 0 op_sel_hi:[1,0]
	v_pk_add_f32 v[28:29], v[26:27], 0 op_sel_hi:[1,0]
	v_cvt_pk_bf16_f32 v26, v34, v35
	v_cvt_pk_bf16_f32 v27, v32, v33
	v_add_co_u32_e32 v32, vcc, s16, v140
	v_cvt_pk_bf16_f32 v28, v28, v29
	v_cvt_pk_bf16_f32 v29, v36, v37
	s_mov_b64 s[16:17], 0x58000
	s_nop 0
	v_addc_co_u32_e32 v33, vcc, 0, v141, vcc
	ds_bpermute_b32 v26, v248, v26
	ds_bpermute_b32 v27, v248, v27
	ds_bpermute_b32 v28, v248, v28
	ds_bpermute_b32 v29, v248, v29
	s_waitcnt lgkmcnt(0)
	global_store_dwordx4 v[32:33], v[26:29], off
	s_nop 1
	v_pk_add_f32 v[26:27], v[16:17], 0 op_sel_hi:[1,0]
	v_pk_add_f32 v[16:17], v[14:15], 0 op_sel_hi:[1,0]
	v_cvt_pk_bf16_f32 v14, v22, v23
	v_cvt_pk_bf16_f32 v15, v24, v25
	s_nop 0
	v_cvt_pk_bf16_f32 v16, v16, v17
	v_cvt_pk_bf16_f32 v17, v26, v27
	ds_bpermute_b32 v14, v248, v14
	ds_bpermute_b32 v15, v248, v15
	ds_bpermute_b32 v16, v248, v16
	ds_bpermute_b32 v17, v248, v17
	s_waitcnt lgkmcnt(0)
	global_store_dwordx4 v[30:31], v[14:17], off offset:256
	s_nop 1
	v_lshl_add_u64 v[14:15], v[140:141], 0, s[16:17]
	v_pk_add_f32 v[16:17], v[20:21], 0 op_sel_hi:[1,0]
	s_mov_b32 s16, 0x58000
	v_pk_add_f32 v[20:21], v[12:13], 0 op_sel_hi:[1,0]
	v_pk_add_f32 v[12:13], v[10:11], 0 op_sel_hi:[1,0]
	v_cvt_pk_bf16_f32 v10, v18, v19
	v_cvt_pk_bf16_f32 v11, v16, v17
	v_add_co_u32_e32 v16, vcc, s16, v140
	v_cvt_pk_bf16_f32 v12, v12, v13
	v_cvt_pk_bf16_f32 v13, v20, v21
	s_mov_b64 s[16:17], -1
	s_nop 0
	v_addc_co_u32_e32 v17, vcc, 0, v141, vcc
	ds_bpermute_b32 v10, v248, v10
	ds_bpermute_b32 v11, v248, v11
	ds_bpermute_b32 v12, v248, v12
	ds_bpermute_b32 v13, v248, v13
	s_waitcnt lgkmcnt(0)
	global_store_dwordx4 v[16:17], v[10:13], off
	s_and_b64 vcc, exec, s[36:37]
	s_nop 0
	v_pk_add_f32 v[10:11], v[4:5], 0 op_sel_hi:[1,0]
	v_pk_add_f32 v[4:5], v[2:3], 0 op_sel_hi:[1,0]
	v_cvt_pk_bf16_f32 v2, v6, v7
	v_cvt_pk_bf16_f32 v3, v8, v9
	s_nop 0
	v_cvt_pk_bf16_f32 v4, v4, v5
	v_cvt_pk_bf16_f32 v5, v10, v11
	ds_bpermute_b32 v2, v248, v2
	ds_bpermute_b32 v3, v248, v3
	ds_bpermute_b32 v4, v248, v4
	ds_bpermute_b32 v5, v248, v5
	s_waitcnt lgkmcnt(0)
	global_store_dwordx4 v[14:15], v[2:5], off offset:256
	s_cbranch_vccnz .LBB0_644
	s_andn2_b64 vcc, exec, s[40:41]
	s_cbranch_vccnz .LBB0_643
	s_barrier
	s_branch .LBB0_643

; __global__ void __launch_bounds__(512, 2) fwd_kernel(Args a) {
	.amdhsa_kernel _Z10fwd_kernel4Args
		.amdhsa_group_segment_fixed_size 0
		.amdhsa_private_segment_fixed_size 0
		.amdhsa_kernarg_size 416
		.amdhsa_user_sgpr_count 2
		.amdhsa_user_sgpr_dispatch_ptr 0
		.amdhsa_user_sgpr_queue_ptr 0
		.amdhsa_user_sgpr_kernarg_segment_ptr 1
		.amdhsa_user_sgpr_dispatch_id 0
		.amdhsa_user_sgpr_kernarg_preload_length 0
		.amdhsa_user_sgpr_kernarg_preload_offset 0
		.amdhsa_user_sgpr_private_segment_size 0
		.amdhsa_uses_dynamic_stack 0
		.amdhsa_enable_private_segment 0
		.amdhsa_system_sgpr_workgroup_id_x 1
		.amdhsa_system_sgpr_workgroup_id_y 0
		.amdhsa_system_sgpr_workgroup_id_z 0
		.amdhsa_system_sgpr_workgroup_info 0
		.amdhsa_system_vgpr_workitem_id 2
		.amdhsa_next_free_vgpr 250
		.amdhsa_next_free_sgpr 98
		.amdhsa_accum_offset 252
		.amdhsa_reserve_vcc 1
		.amdhsa_float_round_mode_32 0
		.amdhsa_float_round_mode_16_64 0
		.amdhsa_float_denorm_mode_32 3
		.amdhsa_float_denorm_mode_16_64 3
		.amdhsa_dx10_clamp 1
		.amdhsa_ieee_mode 1
		.amdhsa_fp16_overflow 0
		.amdhsa_tg_split 0
		.amdhsa_exception_fp_ieee_invalid_op 0
		.amdhsa_exception_fp_denorm_src 0
		.amdhsa_exception_fp_ieee_div_zero 0
		.amdhsa_exception_fp_ieee_overflow 0
		.amdhsa_exception_fp_ieee_underflow 0
		.amdhsa_exception_fp_ieee_inexact 0
		.amdhsa_exception_int_div_zero 0
	.end_amdhsa_kernel

; __global__ void __launch_bounds__(512, 2) fwd_kernel(Args a) {
amdhsa.kernels:
  - .agpr_count:     0
    .args:
      - .offset:         0
        .size:           160
        .value_kind:     by_value
      - .offset:         160
        .size:           4
        .value_kind:     hidden_block_count_x
      - .offset:         164
        .size:           4
        .value_kind:     hidden_block_count_y
      - .offset:         168
        .size:           4
        .value_kind:     hidden_block_count_z
      - .offset:         172
        .size:           2
        .value_kind:     hidden_group_size_x
      - .offset:         174
        .size:           2
        .value_kind:     hidden_group_size_y
      - .offset:         176
        .size:           2
        .value_kind:     hidden_group_size_z
      - .offset:         178
        .size:           2
        .value_kind:     hidden_remainder_x
      - .offset:         180
        .size:           2
        .value_kind:     hidden_remainder_y
      - .offset:         182
        .size:           2
        .value_kind:     hidden_remainder_z
      - .offset:         200
        .size:           8
        .value_kind:     hidden_global_offset_x
      - .offset:         208
        .size:           8
        .value_kind:     hidden_global_offset_y
      - .offset:         216
        .size:           8
        .value_kind:     hidden_global_offset_z
      - .offset:         224
        .size:           2
        .value_kind:     hidden_grid_dims
      - .offset:         248
        .size:           8
        .value_kind:     hidden_multigrid_sync_arg
      - .offset:         280
        .size:           4
        .value_kind:     hidden_dynamic_lds_size
    .group_segment_fixed_size: 0
    .kernarg_segment_align: 8
    .kernarg_segment_size: 416
    .language:       OpenCL C
    .language_version:
      - 2
      - 0
    .max_flat_workgroup_size: 512
    .name:           _Z10fwd_kernel4Args
    .private_segment_fixed_size: 0
    .sgpr_count:     104
    .sgpr_spill_count: 158
    .symbol:         _Z10fwd_kernel4Args.kd
    .uniform_work_group_size: 1
    .uses_dynamic_stack: false
    .vgpr_count:     250
    .vgpr_spill_count: 0
    .wavefront_size: 64
